# write-through (sc1) 16-B stores in w_in/w_up/cmp/w_out epilogues (cheaper release fences at seams) + pipelined w_out residual epilogue
# speedup vs baseline: 1.0517x; 1.0110x over previous
.LBB0_227:
	v_lshl_or_b32 v146, s57, 8, v150
	v_lshl_add_u32 v156, s28, 8, v148
	v_ashrrev_i32_e32 v147, 31, v146
	v_mov_b64_e32 v[144:145], s[4:5]
	v_mad_i64_i32 v[154:155], s[30:31], v156, s56, v[144:145]
	v_lshlrev_b64 v[146:147], 1, v[146:147]
	v_lshl_add_u64 v[154:155], v[154:155], 0, v[146:147]
	v_cvt_pk_bf16_f32 v124, v124, v125
	v_cvt_pk_bf16_f32 v125, v126, v127
	v_cvt_pk_bf16_f32 v126, v120, v121
	v_cvt_pk_bf16_f32 v127, v122, v123
	global_store_dwordx4 v[154:155], v[124:127], off sc1
	v_cvt_pk_bf16_f32 v112, v112, v113
	v_cvt_pk_bf16_f32 v113, v114, v115
	v_cvt_pk_bf16_f32 v114, v104, v105
	v_or_b32_e32 v104, 16, v156
	v_mad_i64_i32 v[104:105], s[30:31], v104, s56, v[144:145]
	v_cvt_pk_bf16_f32 v115, v106, v107
	global_store_dwordx4 v[154:155], v[112:115], off offset:256 sc1
	s_andn2_b64 vcc, exec, s[6:7]
	s_mov_b64 s[6:7], -1
	v_lshl_add_u64 v[112:113], v[104:105], 0, v[146:147]
	v_cvt_pk_bf16_f32 v104, v116, v117
	v_cvt_pk_bf16_f32 v105, v118, v119
	v_cvt_pk_bf16_f32 v106, v108, v109
	v_cvt_pk_bf16_f32 v107, v110, v111
	global_store_dwordx4 v[112:113], v[104:107], off sc1
	v_cvt_pk_bf16_f32 v96, v96, v97
	v_cvt_pk_bf16_f32 v97, v98, v99
	v_cvt_pk_bf16_f32 v98, v88, v89
	v_or_b32_e32 v88, 32, v156
	v_mad_i64_i32 v[88:89], s[30:31], v88, s56, v[144:145]
	v_cvt_pk_bf16_f32 v99, v90, v91
	global_store_dwordx4 v[112:113], v[96:99], off offset:256 sc1
	s_nop 1
	v_lshl_add_u64 v[96:97], v[88:89], 0, v[146:147]
	v_cvt_pk_bf16_f32 v88, v100, v101
	v_cvt_pk_bf16_f32 v89, v102, v103
	v_cvt_pk_bf16_f32 v90, v92, v93
	v_cvt_pk_bf16_f32 v91, v94, v95
	global_store_dwordx4 v[96:97], v[88:91], off sc1
	v_cvt_pk_bf16_f32 v80, v80, v81
	v_cvt_pk_bf16_f32 v81, v82, v83
	v_cvt_pk_bf16_f32 v82, v72, v73
	v_or_b32_e32 v72, 48, v156
	v_mad_i64_i32 v[72:73], s[30:31], v72, s56, v[144:145]
	v_cvt_pk_bf16_f32 v83, v74, v75
	global_store_dwordx4 v[96:97], v[80:83], off offset:256 sc1
	s_nop 1
	v_lshl_add_u64 v[80:81], v[72:73], 0, v[146:147]
	v_cvt_pk_bf16_f32 v72, v84, v85
	v_cvt_pk_bf16_f32 v73, v86, v87
	v_cvt_pk_bf16_f32 v74, v76, v77
	v_cvt_pk_bf16_f32 v75, v78, v79
	global_store_dwordx4 v[80:81], v[72:75], off sc1
	v_cvt_pk_bf16_f32 v68, v68, v69
	v_cvt_pk_bf16_f32 v69, v70, v71
	v_cvt_pk_bf16_f32 v70, v64, v65
	v_add_u32_e32 v64, 0x80, v156
	v_mad_i64_i32 v[64:65], s[30:31], v64, s56, v[144:145]
	v_lshl_add_u64 v[64:65], v[64:65], 0, v[146:147]
	v_cvt_pk_bf16_f32 v71, v66, v67
	global_store_dwordx4 v[80:81], v[68:71], off offset:256 sc1
	v_cvt_pk_bf16_f32 v60, v60, v61
	v_cvt_pk_bf16_f32 v61, v62, v63
	v_cvt_pk_bf16_f32 v62, v56, v57
	v_cvt_pk_bf16_f32 v63, v58, v59
	global_store_dwordx4 v[64:65], v[60:63], off sc1
	v_cvt_pk_bf16_f32 v48, v48, v49
	v_cvt_pk_bf16_f32 v49, v50, v51
	v_cvt_pk_bf16_f32 v50, v40, v41
	v_add_u32_e32 v40, 0x90, v156
	v_mad_i64_i32 v[40:41], s[30:31], v40, s56, v[144:145]
	v_cvt_pk_bf16_f32 v51, v42, v43
	global_store_dwordx4 v[64:65], v[48:51], off offset:256 sc1
	s_nop 1
	v_lshl_add_u64 v[48:49], v[40:41], 0, v[146:147]
	v_cvt_pk_bf16_f32 v40, v52, v53
	v_cvt_pk_bf16_f32 v41, v54, v55
	v_cvt_pk_bf16_f32 v42, v44, v45
	v_cvt_pk_bf16_f32 v43, v46, v47
	global_store_dwordx4 v[48:49], v[40:43], off sc1
	v_cvt_pk_bf16_f32 v32, v32, v33
	v_cvt_pk_bf16_f32 v33, v34, v35
	v_cvt_pk_bf16_f32 v34, v24, v25
	v_add_u32_e32 v24, 0xa0, v156
	v_mad_i64_i32 v[24:25], s[30:31], v24, s56, v[144:145]
	v_cvt_pk_bf16_f32 v35, v26, v27
	global_store_dwordx4 v[48:49], v[32:35], off offset:256 sc1
	s_nop 1
	v_lshl_add_u64 v[32:33], v[24:25], 0, v[146:147]
	v_cvt_pk_bf16_f32 v24, v36, v37
	v_cvt_pk_bf16_f32 v25, v38, v39
	v_cvt_pk_bf16_f32 v26, v28, v29
	v_cvt_pk_bf16_f32 v27, v30, v31
	global_store_dwordx4 v[32:33], v[24:27], off sc1
	v_cvt_pk_bf16_f32 v16, v16, v17
	v_cvt_pk_bf16_f32 v17, v18, v19
	v_cvt_pk_bf16_f32 v18, v8, v9
	v_add_u32_e32 v8, 0xb0, v156
	v_mad_i64_i32 v[8:9], s[30:31], v8, s56, v[144:145]
	v_cvt_pk_bf16_f32 v19, v10, v11
	global_store_dwordx4 v[32:33], v[16:19], off offset:256 sc1
	s_nop 1
	v_lshl_add_u64 v[16:17], v[8:9], 0, v[146:147]
	v_cvt_pk_bf16_f32 v8, v20, v21
	v_cvt_pk_bf16_f32 v9, v22, v23
	v_cvt_pk_bf16_f32 v10, v12, v13
	v_cvt_pk_bf16_f32 v11, v14, v15
	global_store_dwordx4 v[16:17], v[8:11], off sc1
	v_cvt_pk_bf16_f32 v4, v4, v5
	v_cvt_pk_bf16_f32 v5, v6, v7
	v_cvt_pk_bf16_f32 v6, v0, v1
	v_cvt_pk_bf16_f32 v7, v2, v3
	global_store_dwordx4 v[16:17], v[4:7], off offset:256 sc1
	s_cbranch_vccnz .LBB0_220
	s_andn2_b64 vcc, exec, s[2:3]
	s_cbranch_vccnz .LBB0_219
	s_barrier
	s_branch .LBB0_219

.LBB0_365:
	ds_read_b128 v[20:23], v16
	ds_read_b128 v[24:27], v16 offset:1024
	ds_read_b128 v[28:31], v16 offset:2048
	ds_read_b128 v[32:35], v16 offset:3072
	ds_read_b128 v[36:39], v17
	ds_read_b128 v[40:43], v17 offset:1024
	ds_read_b128 v[44:47], v17 offset:2048
	ds_read_b128 v[48:51], v17 offset:3072
	s_add_u32 s30, s33, s26
	s_addc_u32 s31, s42, s27
	s_and_b64 s[34:35], s[2:3], exec
	s_cselect_b32 s41, s31, s37
	s_cselect_b32 s40, s30, s36
	s_add_u32 s34, s43, s28
	s_addc_u32 s35, s44, s29
	s_and_b64 s[2:3], s[2:3], exec
	s_cselect_b32 s3, s35, s39
	s_cselect_b32 s2, s34, s38
	s_add_u32 s64, s36, 0x40080
	s_addc_u32 s65, s37, 0
	s_add_i32 s70, s45, 0xc000
	v_lshl_add_u64 v[84:85], s[64:65], 0, v[6:7]
	s_mov_b32 m0, s70
	ds_read_b128 v[52:55], v18
	ds_read_b128 v[56:59], v18 offset:1024
	ds_read_b128 v[60:63], v18 offset:2048
	ds_read_b128 v[64:67], v18 offset:3072
	ds_read_b128 v[68:71], v18 offset:4096
	ds_read_b128 v[72:75], v18 offset:5120
	ds_read_b128 v[76:79], v18 offset:6144
	ds_read_b128 v[80:83], v18 offset:7168
	global_load_lds_dwordx4 v[84:85], off
	v_lshl_add_u64 v[84:85], s[64:65], 0, v[2:3]
	s_add_i32 s64, s45, 0xe000
	s_mov_b32 m0, s64
	s_nop 0
	global_load_lds_dwordx4 v[84:85], off
	s_waitcnt vmcnt(8)
	s_waitcnt lgkmcnt(0)
	s_barrier
	s_setprio 1
	s_waitcnt lgkmcnt(0)
	v_mfma_f32_16x16x32_bf16 v[84:87], v[20:23], v[52:55], 0
	v_mfma_f32_16x16x32_bf16 v[88:91], v[28:31], v[52:55], 0
	v_mfma_f32_16x16x32_bf16 v[92:95], v[20:23], v[60:63], 0
	v_mfma_f32_16x16x32_bf16 v[96:99], v[28:31], v[60:63], 0
	v_mfma_f32_16x16x32_bf16 v[100:103], v[20:23], v[68:71], 0
	v_mfma_f32_16x16x32_bf16 v[104:107], v[28:31], v[68:71], 0
	v_mfma_f32_16x16x32_bf16 v[108:111], v[20:23], v[76:79], 0
	v_mfma_f32_16x16x32_bf16 v[112:115], v[28:31], v[76:79], 0
	v_mfma_f32_16x16x32_bf16 v[84:87], v[24:27], v[56:59], v[84:87]
	v_mfma_f32_16x16x32_bf16 v[88:91], v[32:35], v[56:59], v[88:91]
	v_mfma_f32_16x16x32_bf16 v[92:95], v[24:27], v[64:67], v[92:95]
	v_mfma_f32_16x16x32_bf16 v[96:99], v[32:35], v[64:67], v[96:99]
	v_mfma_f32_16x16x32_bf16 v[100:103], v[24:27], v[72:75], v[100:103]
	v_mfma_f32_16x16x32_bf16 v[104:107], v[32:35], v[72:75], v[104:107]
	v_mfma_f32_16x16x32_bf16 v[108:111], v[24:27], v[80:83], v[108:111]
	v_mfma_f32_16x16x32_bf16 v[112:115], v[32:35], v[80:83], v[112:115]
	s_setprio 0
	s_setprio 1
	v_mfma_f32_16x16x32_bf16 v[116:119], v[36:39], v[52:55], 0
	v_mfma_f32_16x16x32_bf16 v[52:55], v[44:47], v[52:55], 0
	v_mfma_f32_16x16x32_bf16 v[116:119], v[40:43], v[56:59], v[116:119]
	v_mfma_f32_16x16x32_bf16 v[52:55], v[48:51], v[56:59], v[52:55]
	v_mfma_f32_16x16x32_bf16 v[56:59], v[36:39], v[60:63], 0
	v_mfma_f32_16x16x32_bf16 v[60:63], v[44:47], v[60:63], 0
	v_mfma_f32_16x16x32_bf16 v[56:59], v[40:43], v[64:67], v[56:59]
	v_mfma_f32_16x16x32_bf16 v[60:63], v[48:51], v[64:67], v[60:63]
	v_mfma_f32_16x16x32_bf16 v[64:67], v[36:39], v[68:71], 0
	v_mfma_f32_16x16x32_bf16 v[68:71], v[44:47], v[68:71], 0
	v_mfma_f32_16x16x32_bf16 v[64:67], v[40:43], v[72:75], v[64:67]
	v_mfma_f32_16x16x32_bf16 v[68:71], v[48:51], v[72:75], v[68:71]
	v_mfma_f32_16x16x32_bf16 v[72:75], v[36:39], v[76:79], 0
	v_mfma_f32_16x16x32_bf16 v[76:79], v[44:47], v[76:79], 0
	v_mfma_f32_16x16x32_bf16 v[72:75], v[40:43], v[80:83], v[72:75]
	v_mfma_f32_16x16x32_bf16 v[76:79], v[48:51], v[80:83], v[76:79]
	s_setprio 0
	s_barrier
	v_readlane_b32 s78, v247, 11
	s_add_i32 s68, s57, s78
	v_lshl_add_u64 v[212:213], s[38:39], 0, v[4:5]
	s_add_i32 s65, s68, 0x2000
	v_lshl_add_u64 v[148:149], v[212:213], 0, s[8:9]
	s_mov_b32 m0, s68
	v_lshl_add_u64 v[214:215], s[38:39], 0, v[0:1]
	s_add_u32 s72, s38, 0x80100
	ds_read_b128 v[80:83], v18 offset:16384
	ds_read_b128 v[120:123], v18 offset:17408
	ds_read_b128 v[124:127], v18 offset:18432
	ds_read_b128 v[128:131], v18 offset:19456
	ds_read_b128 v[132:135], v18 offset:20480
	ds_read_b128 v[136:139], v18 offset:21504
	ds_read_b128 v[140:143], v18 offset:22528
	ds_read_b128 v[144:147], v18 offset:23552
	global_load_lds_dwordx4 v[148:149], off
	v_lshl_add_u64 v[148:149], v[214:215], 0, s[8:9]
	s_mov_b32 m0, s65
	s_addc_u32 s73, s39, 0
	s_add_i32 s66, s58, s78
	global_load_lds_dwordx4 v[148:149], off
	v_lshl_add_u64 v[148:149], s[72:73], 0, v[4:5]
	s_mov_b32 m0, s66
	s_add_i32 s67, s66, 0x2000
	global_load_lds_dwordx4 v[148:149], off
	v_lshl_add_u64 v[148:149], s[72:73], 0, v[0:1]
	s_mov_b32 m0, s67
	v_lshl_add_u64 v[216:217], s[36:37], 0, v[6:7]
	global_load_lds_dwordx4 v[148:149], off
	v_lshl_add_u64 v[148:149], v[216:217], 0, s[8:9]
	s_mov_b32 m0, s45
	v_lshl_add_u64 v[218:219], s[36:37], 0, v[2:3]
	global_load_lds_dwordx4 v[148:149], off
	v_lshl_add_u64 v[148:149], v[218:219], 0, s[8:9]
	s_mov_b32 m0, s46
	s_nop 0
	global_load_lds_dwordx4 v[148:149], off
	s_waitcnt vmcnt(8)
	s_waitcnt lgkmcnt(0)
	s_barrier
	s_setprio 1
	s_waitcnt lgkmcnt(0)
	v_mfma_f32_16x16x32_bf16 v[148:151], v[20:23], v[80:83], 0
	v_mfma_f32_16x16x32_bf16 v[156:159], v[20:23], v[124:127], 0
	v_mfma_f32_16x16x32_bf16 v[164:167], v[20:23], v[132:135], 0
	v_mfma_f32_16x16x32_bf16 v[20:23], v[20:23], v[140:143], 0
	v_mfma_f32_16x16x32_bf16 v[148:151], v[24:27], v[120:123], v[148:151]
	v_mfma_f32_16x16x32_bf16 v[152:155], v[28:31], v[80:83], 0
	v_mfma_f32_16x16x32_bf16 v[156:159], v[24:27], v[128:131], v[156:159]
	v_mfma_f32_16x16x32_bf16 v[160:163], v[28:31], v[124:127], 0
	v_mfma_f32_16x16x32_bf16 v[164:167], v[24:27], v[136:139], v[164:167]
	v_mfma_f32_16x16x32_bf16 v[168:171], v[28:31], v[132:135], 0
	v_mfma_f32_16x16x32_bf16 v[20:23], v[24:27], v[144:147], v[20:23]
	v_mfma_f32_16x16x32_bf16 v[24:27], v[28:31], v[140:143], 0
	v_mfma_f32_16x16x32_bf16 v[152:155], v[32:35], v[120:123], v[152:155]
	v_mfma_f32_16x16x32_bf16 v[160:163], v[32:35], v[128:131], v[160:163]
	v_mfma_f32_16x16x32_bf16 v[168:171], v[32:35], v[136:139], v[168:171]
	v_mfma_f32_16x16x32_bf16 v[24:27], v[32:35], v[144:147], v[24:27]
	s_setprio 0
	s_setprio 1
	v_mfma_f32_16x16x32_bf16 v[28:31], v[36:39], v[80:83], 0
	v_mfma_f32_16x16x32_bf16 v[32:35], v[44:47], v[80:83], 0
	v_mfma_f32_16x16x32_bf16 v[28:31], v[40:43], v[120:123], v[28:31]
	v_mfma_f32_16x16x32_bf16 v[32:35], v[48:51], v[120:123], v[32:35]
	v_mfma_f32_16x16x32_bf16 v[80:83], v[36:39], v[124:127], 0
	v_mfma_f32_16x16x32_bf16 v[120:123], v[44:47], v[124:127], 0
	v_mfma_f32_16x16x32_bf16 v[124:127], v[36:39], v[132:135], 0
	v_mfma_f32_16x16x32_bf16 v[36:39], v[36:39], v[140:143], 0
	v_mfma_f32_16x16x32_bf16 v[80:83], v[40:43], v[128:131], v[80:83]
	v_mfma_f32_16x16x32_bf16 v[120:123], v[48:51], v[128:131], v[120:123]
	v_mfma_f32_16x16x32_bf16 v[124:127], v[40:43], v[136:139], v[124:127]
	v_mfma_f32_16x16x32_bf16 v[128:131], v[44:47], v[132:135], 0
	v_mfma_f32_16x16x32_bf16 v[36:39], v[40:43], v[144:147], v[36:39]
	v_mfma_f32_16x16x32_bf16 v[40:43], v[44:47], v[140:143], 0
	v_mfma_f32_16x16x32_bf16 v[128:131], v[48:51], v[136:139], v[128:131]
	v_mfma_f32_16x16x32_bf16 v[40:43], v[48:51], v[144:147], v[40:43]
	s_setprio 0
	s_barrier
	s_add_i32 s71, 0, 0x18000
	s_add_i32 s74, 0, 0x1c000
	v_add_u32_e32 v19, s71, v15
	v_add_u32_e32 v222, s74, v15
	ds_read_b128 v[44:47], v19
	ds_read_b128 v[48:51], v19 offset:1024
	ds_read_b128 v[132:135], v19 offset:2048
	ds_read_b128 v[136:139], v19 offset:3072
	ds_read_b128 v[140:143], v222
	ds_read_b128 v[144:147], v222 offset:1024
	ds_read_b128 v[172:175], v222 offset:2048
	ds_read_b128 v[176:179], v222 offset:3072
	s_add_u32 s72, s36, 0x40100
	s_addc_u32 s73, s37, 0
	s_mov_b32 m0, s47
	v_lshl_add_u64 v[220:221], s[72:73], 0, v[6:7]
	ds_read_b128 v[180:183], v18 offset:32768
	ds_read_b128 v[184:187], v18 offset:33792
	ds_read_b128 v[188:191], v18 offset:34816
	ds_read_b128 v[192:195], v18 offset:35840
	ds_read_b128 v[196:199], v18 offset:36864
	ds_read_b128 v[200:203], v18 offset:37888
	ds_read_b128 v[204:207], v18 offset:38912
	ds_read_b128 v[208:211], v18 offset:39936
	global_load_lds_dwordx4 v[220:221], off
	v_lshl_add_u64 v[220:221], s[72:73], 0, v[2:3]
	s_mov_b32 m0, s48
	s_nop 0
	global_load_lds_dwordx4 v[220:221], off
	s_waitcnt vmcnt(8)
	s_waitcnt lgkmcnt(0)
	s_barrier
	s_setprio 1
	s_waitcnt lgkmcnt(0)
	v_mfma_f32_16x16x32_bf16 v[84:87], v[44:47], v[180:183], v[84:87]
	v_mfma_f32_16x16x32_bf16 v[88:91], v[132:135], v[180:183], v[88:91]
	v_mfma_f32_16x16x32_bf16 v[92:95], v[44:47], v[188:191], v[92:95]
	v_mfma_f32_16x16x32_bf16 v[96:99], v[132:135], v[188:191], v[96:99]
	v_mfma_f32_16x16x32_bf16 v[100:103], v[44:47], v[196:199], v[100:103]
	v_mfma_f32_16x16x32_bf16 v[104:107], v[132:135], v[196:199], v[104:107]
	v_mfma_f32_16x16x32_bf16 v[108:111], v[44:47], v[204:207], v[108:111]
	v_mfma_f32_16x16x32_bf16 v[112:115], v[132:135], v[204:207], v[112:115]
	v_mfma_f32_16x16x32_bf16 v[84:87], v[48:51], v[184:187], v[84:87]
	v_mfma_f32_16x16x32_bf16 v[88:91], v[136:139], v[184:187], v[88:91]
	v_mfma_f32_16x16x32_bf16 v[92:95], v[48:51], v[192:195], v[92:95]
	v_mfma_f32_16x16x32_bf16 v[96:99], v[136:139], v[192:195], v[96:99]
	v_mfma_f32_16x16x32_bf16 v[100:103], v[48:51], v[200:203], v[100:103]
	v_mfma_f32_16x16x32_bf16 v[104:107], v[136:139], v[200:203], v[104:107]
	v_mfma_f32_16x16x32_bf16 v[108:111], v[48:51], v[208:211], v[108:111]
	v_mfma_f32_16x16x32_bf16 v[112:115], v[136:139], v[208:211], v[112:115]
	s_setprio 0
	s_setprio 1
	v_mfma_f32_16x16x32_bf16 v[116:119], v[140:143], v[180:183], v[116:119]
	v_mfma_f32_16x16x32_bf16 v[52:55], v[172:175], v[180:183], v[52:55]
	v_mfma_f32_16x16x32_bf16 v[56:59], v[140:143], v[188:191], v[56:59]
	v_mfma_f32_16x16x32_bf16 v[60:63], v[172:175], v[188:191], v[60:63]
	v_mfma_f32_16x16x32_bf16 v[64:67], v[140:143], v[196:199], v[64:67]
	v_mfma_f32_16x16x32_bf16 v[68:71], v[172:175], v[196:199], v[68:71]
	v_mfma_f32_16x16x32_bf16 v[72:75], v[140:143], v[204:207], v[72:75]
	v_mfma_f32_16x16x32_bf16 v[76:79], v[172:175], v[204:207], v[76:79]
	v_mfma_f32_16x16x32_bf16 v[116:119], v[144:147], v[184:187], v[116:119]
	v_mfma_f32_16x16x32_bf16 v[52:55], v[176:179], v[184:187], v[52:55]
	v_mfma_f32_16x16x32_bf16 v[56:59], v[144:147], v[192:195], v[56:59]
	v_mfma_f32_16x16x32_bf16 v[60:63], v[176:179], v[192:195], v[60:63]
	v_mfma_f32_16x16x32_bf16 v[64:67], v[144:147], v[200:203], v[64:67]
	v_mfma_f32_16x16x32_bf16 v[68:71], v[176:179], v[200:203], v[68:71]
	v_mfma_f32_16x16x32_bf16 v[72:75], v[144:147], v[208:211], v[72:75]
	v_mfma_f32_16x16x32_bf16 v[76:79], v[176:179], v[208:211], v[76:79]
	s_setprio 0
	s_barrier
	s_add_i32 s71, s71, s78
	s_add_i32 s69, s71, 0x2000
	v_lshl_add_u64 v[212:213], v[212:213], 0, s[10:11]
	s_mov_b32 m0, s71
	s_add_u32 s72, s38, 0x80180
	ds_read_b128 v[180:183], v18 offset:49152
	ds_read_b128 v[184:187], v18 offset:50176
	ds_read_b128 v[188:191], v18 offset:51200
	ds_read_b128 v[192:195], v18 offset:52224
	ds_read_b128 v[196:199], v18 offset:53248
	ds_read_b128 v[200:203], v18 offset:54272
	ds_read_b128 v[204:207], v18 offset:55296
	ds_read_b128 v[208:211], v18 offset:56320
	global_load_lds_dwordx4 v[212:213], off
	v_lshl_add_u64 v[212:213], v[214:215], 0, s[10:11]
	s_mov_b32 m0, s69
	s_addc_u32 s73, s39, 0
	s_add_i32 s38, s74, s78
	global_load_lds_dwordx4 v[212:213], off
	v_lshl_add_u64 v[212:213], s[72:73], 0, v[4:5]
	s_mov_b32 m0, s38
	s_add_i32 s39, s38, 0x2000
	global_load_lds_dwordx4 v[212:213], off
	v_lshl_add_u64 v[212:213], s[72:73], 0, v[0:1]
	s_mov_b32 m0, s39
	s_nop 0
	global_load_lds_dwordx4 v[212:213], off
	v_lshl_add_u64 v[212:213], v[216:217], 0, s[10:11]
	s_mov_b32 m0, s52
	s_nop 0
	global_load_lds_dwordx4 v[212:213], off
	v_lshl_add_u64 v[212:213], v[218:219], 0, s[10:11]
	s_mov_b32 m0, s53
	s_nop 0
	global_load_lds_dwordx4 v[212:213], off
	s_waitcnt vmcnt(8)
	s_waitcnt lgkmcnt(0)
	s_barrier
	s_setprio 1
	s_waitcnt lgkmcnt(0)
	v_mfma_f32_16x16x32_bf16 v[148:151], v[44:47], v[180:183], v[148:151]
	v_mfma_f32_16x16x32_bf16 v[152:155], v[132:135], v[180:183], v[152:155]
	v_mfma_f32_16x16x32_bf16 v[156:159], v[44:47], v[188:191], v[156:159]
	v_mfma_f32_16x16x32_bf16 v[160:163], v[132:135], v[188:191], v[160:163]
	v_mfma_f32_16x16x32_bf16 v[164:167], v[44:47], v[196:199], v[164:167]
	v_mfma_f32_16x16x32_bf16 v[168:171], v[132:135], v[196:199], v[168:171]
	v_mfma_f32_16x16x32_bf16 v[20:23], v[44:47], v[204:207], v[20:23]
	v_mfma_f32_16x16x32_bf16 v[24:27], v[132:135], v[204:207], v[24:27]
	v_mfma_f32_16x16x32_bf16 v[148:151], v[48:51], v[184:187], v[148:151]
	v_mfma_f32_16x16x32_bf16 v[152:155], v[136:139], v[184:187], v[152:155]
	v_mfma_f32_16x16x32_bf16 v[156:159], v[48:51], v[192:195], v[156:159]
	v_mfma_f32_16x16x32_bf16 v[160:163], v[136:139], v[192:195], v[160:163]
	v_mfma_f32_16x16x32_bf16 v[164:167], v[48:51], v[200:203], v[164:167]
	v_mfma_f32_16x16x32_bf16 v[168:171], v[136:139], v[200:203], v[168:171]
	v_mfma_f32_16x16x32_bf16 v[20:23], v[48:51], v[208:211], v[20:23]
	v_mfma_f32_16x16x32_bf16 v[24:27], v[136:139], v[208:211], v[24:27]
	s_setprio 0
	s_setprio 1
	v_mfma_f32_16x16x32_bf16 v[28:31], v[140:143], v[180:183], v[28:31]
	v_mfma_f32_16x16x32_bf16 v[32:35], v[172:175], v[180:183], v[32:35]
	v_mfma_f32_16x16x32_bf16 v[44:47], v[140:143], v[188:191], v[80:83]
	v_mfma_f32_16x16x32_bf16 v[48:51], v[172:175], v[188:191], v[120:123]
	v_mfma_f32_16x16x32_bf16 v[80:83], v[140:143], v[196:199], v[124:127]
	v_mfma_f32_16x16x32_bf16 v[120:123], v[172:175], v[196:199], v[128:131]
	v_mfma_f32_16x16x32_bf16 v[36:39], v[140:143], v[204:207], v[36:39]
	v_mfma_f32_16x16x32_bf16 v[40:43], v[172:175], v[204:207], v[40:43]
	v_mfma_f32_16x16x32_bf16 v[28:31], v[144:147], v[184:187], v[28:31]
	v_mfma_f32_16x16x32_bf16 v[32:35], v[176:179], v[184:187], v[32:35]
	v_mfma_f32_16x16x32_bf16 v[44:47], v[144:147], v[192:195], v[44:47]
	v_mfma_f32_16x16x32_bf16 v[48:51], v[176:179], v[192:195], v[48:51]
	v_mfma_f32_16x16x32_bf16 v[80:83], v[144:147], v[200:203], v[80:83]
	v_mfma_f32_16x16x32_bf16 v[120:123], v[176:179], v[200:203], v[120:123]
	v_mfma_f32_16x16x32_bf16 v[36:39], v[144:147], v[208:211], v[36:39]
	v_mfma_f32_16x16x32_bf16 v[40:43], v[176:179], v[208:211], v[40:43]
	s_setprio 0
	s_barrier
	ds_read_b128 v[124:127], v16
	ds_read_b128 v[128:131], v16 offset:1024
	ds_read_b128 v[132:135], v16 offset:2048
	ds_read_b128 v[136:139], v16 offset:3072
	ds_read_b128 v[140:143], v17
	ds_read_b128 v[144:147], v17 offset:1024
	ds_read_b128 v[172:175], v17 offset:2048
	ds_read_b128 v[176:179], v17 offset:3072
	s_add_u32 s36, s36, 0x40180
	s_addc_u32 s37, s37, 0
	s_mov_b32 m0, s70
	v_lshl_add_u64 v[212:213], s[36:37], 0, v[6:7]
	ds_read_b128 v[180:183], v18
	ds_read_b128 v[184:187], v18 offset:1024
	ds_read_b128 v[188:191], v18 offset:2048
	ds_read_b128 v[192:195], v18 offset:3072
	ds_read_b128 v[196:199], v18 offset:4096
	ds_read_b128 v[200:203], v18 offset:5120
	ds_read_b128 v[204:207], v18 offset:6144
	ds_read_b128 v[208:211], v18 offset:7168
	global_load_lds_dwordx4 v[212:213], off
	v_lshl_add_u64 v[212:213], s[36:37], 0, v[2:3]
	s_mov_b32 m0, s64
	s_nop 0
	global_load_lds_dwordx4 v[212:213], off
	s_waitcnt vmcnt(8)
	s_waitcnt lgkmcnt(0)
	s_barrier
	s_setprio 1
	s_waitcnt lgkmcnt(0)
	v_mfma_f32_16x16x32_bf16 v[84:87], v[124:127], v[180:183], v[84:87]
	v_mfma_f32_16x16x32_bf16 v[88:91], v[132:135], v[180:183], v[88:91]
	v_mfma_f32_16x16x32_bf16 v[92:95], v[124:127], v[188:191], v[92:95]
	v_mfma_f32_16x16x32_bf16 v[96:99], v[132:135], v[188:191], v[96:99]
	v_mfma_f32_16x16x32_bf16 v[100:103], v[124:127], v[196:199], v[100:103]
	v_mfma_f32_16x16x32_bf16 v[104:107], v[132:135], v[196:199], v[104:107]
	v_mfma_f32_16x16x32_bf16 v[108:111], v[124:127], v[204:207], v[108:111]
	v_mfma_f32_16x16x32_bf16 v[112:115], v[132:135], v[204:207], v[112:115]
	v_mfma_f32_16x16x32_bf16 v[84:87], v[128:131], v[184:187], v[84:87]
	v_mfma_f32_16x16x32_bf16 v[88:91], v[136:139], v[184:187], v[88:91]
	v_mfma_f32_16x16x32_bf16 v[92:95], v[128:131], v[192:195], v[92:95]
	v_mfma_f32_16x16x32_bf16 v[96:99], v[136:139], v[192:195], v[96:99]
	v_mfma_f32_16x16x32_bf16 v[100:103], v[128:131], v[200:203], v[100:103]
	v_mfma_f32_16x16x32_bf16 v[104:107], v[136:139], v[200:203], v[104:107]
	v_mfma_f32_16x16x32_bf16 v[108:111], v[128:131], v[208:211], v[108:111]
	v_mfma_f32_16x16x32_bf16 v[112:115], v[136:139], v[208:211], v[112:115]
	s_setprio 0
	s_setprio 1
	v_mfma_f32_16x16x32_bf16 v[116:119], v[140:143], v[180:183], v[116:119]
	v_mfma_f32_16x16x32_bf16 v[52:55], v[172:175], v[180:183], v[52:55]
	v_mfma_f32_16x16x32_bf16 v[56:59], v[140:143], v[188:191], v[56:59]
	v_mfma_f32_16x16x32_bf16 v[60:63], v[172:175], v[188:191], v[60:63]
	v_mfma_f32_16x16x32_bf16 v[64:67], v[140:143], v[196:199], v[64:67]
	v_mfma_f32_16x16x32_bf16 v[68:71], v[172:175], v[196:199], v[68:71]
	v_mfma_f32_16x16x32_bf16 v[72:75], v[140:143], v[204:207], v[72:75]
	v_mfma_f32_16x16x32_bf16 v[76:79], v[172:175], v[204:207], v[76:79]
	v_mfma_f32_16x16x32_bf16 v[116:119], v[144:147], v[184:187], v[116:119]
	v_mfma_f32_16x16x32_bf16 v[52:55], v[176:179], v[184:187], v[52:55]
	v_mfma_f32_16x16x32_bf16 v[56:59], v[144:147], v[192:195], v[56:59]
	v_mfma_f32_16x16x32_bf16 v[60:63], v[176:179], v[192:195], v[60:63]
	v_mfma_f32_16x16x32_bf16 v[64:67], v[144:147], v[200:203], v[64:67]
	v_mfma_f32_16x16x32_bf16 v[68:71], v[176:179], v[200:203], v[68:71]
	v_mfma_f32_16x16x32_bf16 v[72:75], v[144:147], v[208:211], v[72:75]
	v_mfma_f32_16x16x32_bf16 v[76:79], v[176:179], v[208:211], v[76:79]
	s_setprio 0
	s_barrier
	s_mov_b32 m0, s68
	v_lshl_add_u64 v[212:213], s[2:3], 0, v[4:5]
	s_add_u32 s36, s2, 0x80000
	ds_read_b128 v[180:183], v18 offset:16384
	ds_read_b128 v[184:187], v18 offset:17408
	ds_read_b128 v[188:191], v18 offset:18432
	ds_read_b128 v[192:195], v18 offset:19456
	ds_read_b128 v[196:199], v18 offset:20480
	ds_read_b128 v[200:203], v18 offset:21504
	ds_read_b128 v[204:207], v18 offset:22528
	ds_read_b128 v[208:211], v18 offset:23552
	global_load_lds_dwordx4 v[212:213], off
	v_lshl_add_u64 v[214:215], s[2:3], 0, v[0:1]
	s_mov_b32 m0, s65
	s_addc_u32 s37, s3, 0
	global_load_lds_dwordx4 v[214:215], off
	v_lshl_add_u64 v[216:217], s[36:37], 0, v[4:5]
	s_mov_b32 m0, s66
	v_lshl_add_u64 v[218:219], s[40:41], 0, v[2:3]
	global_load_lds_dwordx4 v[216:217], off
	v_lshl_add_u64 v[216:217], s[36:37], 0, v[0:1]
	s_mov_b32 m0, s67
	s_nop 0
	global_load_lds_dwordx4 v[216:217], off
	v_lshl_add_u64 v[216:217], s[40:41], 0, v[6:7]
	s_mov_b32 m0, s45
	s_nop 0
	global_load_lds_dwordx4 v[216:217], off
	s_mov_b32 m0, s46
	s_nop 0
	global_load_lds_dwordx4 v[218:219], off
	s_waitcnt vmcnt(8)
	s_waitcnt lgkmcnt(0)
	s_barrier
	s_setprio 1
	s_waitcnt lgkmcnt(0)
	v_mfma_f32_16x16x32_bf16 v[148:151], v[124:127], v[180:183], v[148:151]
	v_mfma_f32_16x16x32_bf16 v[152:155], v[132:135], v[180:183], v[152:155]
	v_mfma_f32_16x16x32_bf16 v[156:159], v[124:127], v[188:191], v[156:159]
	v_mfma_f32_16x16x32_bf16 v[160:163], v[132:135], v[188:191], v[160:163]
	v_mfma_f32_16x16x32_bf16 v[164:167], v[124:127], v[196:199], v[164:167]
	v_mfma_f32_16x16x32_bf16 v[168:171], v[132:135], v[196:199], v[168:171]
	v_mfma_f32_16x16x32_bf16 v[20:23], v[124:127], v[204:207], v[20:23]
	v_mfma_f32_16x16x32_bf16 v[24:27], v[132:135], v[204:207], v[24:27]
	v_mfma_f32_16x16x32_bf16 v[148:151], v[128:131], v[184:187], v[148:151]
	v_mfma_f32_16x16x32_bf16 v[152:155], v[136:139], v[184:187], v[152:155]
	v_mfma_f32_16x16x32_bf16 v[156:159], v[128:131], v[192:195], v[156:159]
	v_mfma_f32_16x16x32_bf16 v[160:163], v[136:139], v[192:195], v[160:163]
	v_mfma_f32_16x16x32_bf16 v[164:167], v[128:131], v[200:203], v[164:167]
	v_mfma_f32_16x16x32_bf16 v[168:171], v[136:139], v[200:203], v[168:171]
	v_mfma_f32_16x16x32_bf16 v[20:23], v[128:131], v[208:211], v[20:23]
	v_mfma_f32_16x16x32_bf16 v[24:27], v[136:139], v[208:211], v[24:27]
	s_setprio 0
	s_setprio 1
	v_mfma_f32_16x16x32_bf16 v[28:31], v[140:143], v[180:183], v[28:31]
	v_mfma_f32_16x16x32_bf16 v[32:35], v[172:175], v[180:183], v[32:35]
	v_mfma_f32_16x16x32_bf16 v[44:47], v[140:143], v[188:191], v[44:47]
	v_mfma_f32_16x16x32_bf16 v[48:51], v[172:175], v[188:191], v[48:51]
	v_mfma_f32_16x16x32_bf16 v[80:83], v[140:143], v[196:199], v[80:83]
	v_mfma_f32_16x16x32_bf16 v[120:123], v[172:175], v[196:199], v[120:123]
	v_mfma_f32_16x16x32_bf16 v[36:39], v[140:143], v[204:207], v[36:39]
	v_mfma_f32_16x16x32_bf16 v[40:43], v[172:175], v[204:207], v[40:43]
	v_mfma_f32_16x16x32_bf16 v[28:31], v[144:147], v[184:187], v[28:31]
	v_mfma_f32_16x16x32_bf16 v[32:35], v[176:179], v[184:187], v[32:35]
	v_mfma_f32_16x16x32_bf16 v[44:47], v[144:147], v[192:195], v[44:47]
	v_mfma_f32_16x16x32_bf16 v[48:51], v[176:179], v[192:195], v[48:51]
	v_mfma_f32_16x16x32_bf16 v[80:83], v[144:147], v[200:203], v[80:83]
	v_mfma_f32_16x16x32_bf16 v[120:123], v[176:179], v[200:203], v[120:123]
	v_mfma_f32_16x16x32_bf16 v[36:39], v[144:147], v[208:211], v[36:39]
	v_mfma_f32_16x16x32_bf16 v[40:43], v[176:179], v[208:211], v[40:43]
	s_setprio 0
	s_barrier
	ds_read_b128 v[124:127], v19
	ds_read_b128 v[128:131], v19 offset:1024
	ds_read_b128 v[132:135], v19 offset:2048
	ds_read_b128 v[136:139], v19 offset:3072
	ds_read_b128 v[140:143], v222
	ds_read_b128 v[144:147], v222 offset:1024
	ds_read_b128 v[172:175], v222 offset:2048
	ds_read_b128 v[176:179], v222 offset:3072
	s_add_u32 s36, s40, 0x40000
	s_addc_u32 s37, s41, 0
	s_mov_b32 m0, s47
	v_lshl_add_u64 v[220:221], s[36:37], 0, v[6:7]
	ds_read_b128 v[180:183], v18 offset:32768
	ds_read_b128 v[184:187], v18 offset:33792
	ds_read_b128 v[188:191], v18 offset:34816
	ds_read_b128 v[192:195], v18 offset:35840
	ds_read_b128 v[196:199], v18 offset:36864
	ds_read_b128 v[200:203], v18 offset:37888
	ds_read_b128 v[204:207], v18 offset:38912
	ds_read_b128 v[208:211], v18 offset:39936
	global_load_lds_dwordx4 v[220:221], off
	v_lshl_add_u64 v[220:221], s[36:37], 0, v[2:3]
	s_mov_b32 m0, s48
	s_nop 0
	global_load_lds_dwordx4 v[220:221], off
	s_waitcnt vmcnt(8)
	s_waitcnt lgkmcnt(0)
	s_barrier
	s_setprio 1
	s_waitcnt lgkmcnt(0)
	v_mfma_f32_16x16x32_bf16 v[84:87], v[124:127], v[180:183], v[84:87]
	v_mfma_f32_16x16x32_bf16 v[88:91], v[132:135], v[180:183], v[88:91]
	v_mfma_f32_16x16x32_bf16 v[92:95], v[124:127], v[188:191], v[92:95]
	v_mfma_f32_16x16x32_bf16 v[96:99], v[132:135], v[188:191], v[96:99]
	v_mfma_f32_16x16x32_bf16 v[100:103], v[124:127], v[196:199], v[100:103]
	v_mfma_f32_16x16x32_bf16 v[104:107], v[132:135], v[196:199], v[104:107]
	v_mfma_f32_16x16x32_bf16 v[108:111], v[124:127], v[204:207], v[108:111]
	v_mfma_f32_16x16x32_bf16 v[112:115], v[132:135], v[204:207], v[112:115]
	v_mfma_f32_16x16x32_bf16 v[84:87], v[128:131], v[184:187], v[84:87]
	v_mfma_f32_16x16x32_bf16 v[88:91], v[136:139], v[184:187], v[88:91]
	v_mfma_f32_16x16x32_bf16 v[92:95], v[128:131], v[192:195], v[92:95]
	v_mfma_f32_16x16x32_bf16 v[96:99], v[136:139], v[192:195], v[96:99]
	v_mfma_f32_16x16x32_bf16 v[100:103], v[128:131], v[200:203], v[100:103]
	v_mfma_f32_16x16x32_bf16 v[104:107], v[136:139], v[200:203], v[104:107]
	v_mfma_f32_16x16x32_bf16 v[108:111], v[128:131], v[208:211], v[108:111]
	v_mfma_f32_16x16x32_bf16 v[112:115], v[136:139], v[208:211], v[112:115]
	s_setprio 0
	s_setprio 1
	v_mfma_f32_16x16x32_bf16 v[116:119], v[140:143], v[180:183], v[116:119]
	v_mfma_f32_16x16x32_bf16 v[52:55], v[172:175], v[180:183], v[52:55]
	v_mfma_f32_16x16x32_bf16 v[56:59], v[140:143], v[188:191], v[56:59]
	v_mfma_f32_16x16x32_bf16 v[60:63], v[172:175], v[188:191], v[60:63]
	v_mfma_f32_16x16x32_bf16 v[64:67], v[140:143], v[196:199], v[64:67]
	v_mfma_f32_16x16x32_bf16 v[68:71], v[172:175], v[196:199], v[68:71]
	v_mfma_f32_16x16x32_bf16 v[72:75], v[140:143], v[204:207], v[72:75]
	v_mfma_f32_16x16x32_bf16 v[76:79], v[172:175], v[204:207], v[76:79]
	v_mfma_f32_16x16x32_bf16 v[116:119], v[144:147], v[184:187], v[116:119]
	v_mfma_f32_16x16x32_bf16 v[52:55], v[176:179], v[184:187], v[52:55]
	v_mfma_f32_16x16x32_bf16 v[56:59], v[144:147], v[192:195], v[56:59]
	v_mfma_f32_16x16x32_bf16 v[60:63], v[176:179], v[192:195], v[60:63]
	v_mfma_f32_16x16x32_bf16 v[64:67], v[144:147], v[200:203], v[64:67]
	v_mfma_f32_16x16x32_bf16 v[68:71], v[176:179], v[200:203], v[68:71]
	v_mfma_f32_16x16x32_bf16 v[72:75], v[144:147], v[208:211], v[72:75]
	v_mfma_f32_16x16x32_bf16 v[76:79], v[176:179], v[208:211], v[76:79]
	s_setprio 0
	s_barrier
	s_mov_b32 m0, s71
	v_lshl_add_u64 v[212:213], v[212:213], 0, s[4:5]
	s_add_u32 s2, s2, 0x80080
	ds_read_b128 v[180:183], v18 offset:49152
	ds_read_b128 v[184:187], v18 offset:50176
	ds_read_b128 v[188:191], v18 offset:51200
	ds_read_b128 v[192:195], v18 offset:52224
	ds_read_b128 v[196:199], v18 offset:53248
	ds_read_b128 v[200:203], v18 offset:54272
	ds_read_b128 v[204:207], v18 offset:55296
	ds_read_b128 v[208:211], v18 offset:56320
	global_load_lds_dwordx4 v[212:213], off
	v_lshl_add_u64 v[212:213], v[214:215], 0, s[4:5]
	s_mov_b32 m0, s69
	s_addc_u32 s3, s3, 0
	global_load_lds_dwordx4 v[212:213], off
	v_lshl_add_u64 v[212:213], s[2:3], 0, v[4:5]
	s_mov_b32 m0, s38
	s_nop 0
	global_load_lds_dwordx4 v[212:213], off
	v_lshl_add_u64 v[212:213], s[2:3], 0, v[0:1]
	s_mov_b32 m0, s39
	s_nop 0
	global_load_lds_dwordx4 v[212:213], off
	v_lshl_add_u64 v[212:213], v[216:217], 0, s[4:5]
	s_mov_b32 m0, s52
	s_nop 0
	global_load_lds_dwordx4 v[212:213], off
	v_lshl_add_u64 v[212:213], v[218:219], 0, s[4:5]
	s_mov_b32 m0, s53
	s_nop 0
	global_load_lds_dwordx4 v[212:213], off
	s_waitcnt vmcnt(8)
	s_waitcnt lgkmcnt(0)
	s_barrier
	s_setprio 1
	s_waitcnt lgkmcnt(0)
	v_mfma_f32_16x16x32_bf16 v[148:151], v[124:127], v[180:183], v[148:151]
	v_mfma_f32_16x16x32_bf16 v[152:155], v[132:135], v[180:183], v[152:155]
	v_mfma_f32_16x16x32_bf16 v[156:159], v[124:127], v[188:191], v[156:159]
	v_mfma_f32_16x16x32_bf16 v[160:163], v[132:135], v[188:191], v[160:163]
	v_mfma_f32_16x16x32_bf16 v[164:167], v[124:127], v[196:199], v[164:167]
	v_mfma_f32_16x16x32_bf16 v[168:171], v[132:135], v[196:199], v[168:171]
	v_mfma_f32_16x16x32_bf16 v[20:23], v[124:127], v[204:207], v[20:23]
	v_mfma_f32_16x16x32_bf16 v[24:27], v[132:135], v[204:207], v[24:27]
	v_mfma_f32_16x16x32_bf16 v[148:151], v[128:131], v[184:187], v[148:151]
	v_mfma_f32_16x16x32_bf16 v[152:155], v[136:139], v[184:187], v[152:155]
	v_mfma_f32_16x16x32_bf16 v[156:159], v[128:131], v[192:195], v[156:159]
	v_mfma_f32_16x16x32_bf16 v[160:163], v[136:139], v[192:195], v[160:163]
	v_mfma_f32_16x16x32_bf16 v[164:167], v[128:131], v[200:203], v[164:167]
	v_mfma_f32_16x16x32_bf16 v[168:171], v[136:139], v[200:203], v[168:171]
	v_mfma_f32_16x16x32_bf16 v[20:23], v[128:131], v[208:211], v[20:23]
	v_mfma_f32_16x16x32_bf16 v[24:27], v[136:139], v[208:211], v[24:27]
	s_setprio 0
	s_setprio 1
	v_mfma_f32_16x16x32_bf16 v[28:31], v[140:143], v[180:183], v[28:31]
	v_mfma_f32_16x16x32_bf16 v[32:35], v[172:175], v[180:183], v[32:35]
	v_mfma_f32_16x16x32_bf16 v[44:47], v[140:143], v[188:191], v[44:47]
	v_mfma_f32_16x16x32_bf16 v[48:51], v[172:175], v[188:191], v[48:51]
	v_mfma_f32_16x16x32_bf16 v[80:83], v[140:143], v[196:199], v[80:83]
	v_mfma_f32_16x16x32_bf16 v[120:123], v[172:175], v[196:199], v[120:123]
	v_mfma_f32_16x16x32_bf16 v[36:39], v[140:143], v[204:207], v[36:39]
	v_mfma_f32_16x16x32_bf16 v[40:43], v[172:175], v[204:207], v[40:43]
	v_mfma_f32_16x16x32_bf16 v[28:31], v[144:147], v[184:187], v[28:31]
	v_mfma_f32_16x16x32_bf16 v[32:35], v[176:179], v[184:187], v[32:35]
	v_mfma_f32_16x16x32_bf16 v[44:47], v[144:147], v[192:195], v[44:47]
	v_mfma_f32_16x16x32_bf16 v[48:51], v[176:179], v[192:195], v[48:51]
	v_mfma_f32_16x16x32_bf16 v[80:83], v[144:147], v[200:203], v[80:83]
	v_mfma_f32_16x16x32_bf16 v[120:123], v[176:179], v[200:203], v[120:123]
	v_mfma_f32_16x16x32_bf16 v[36:39], v[144:147], v[208:211], v[36:39]
	v_mfma_f32_16x16x32_bf16 v[40:43], v[176:179], v[208:211], v[40:43]
	s_setprio 0
	s_barrier
	v_lshl_add_u32 v124, s7, 8, v14
	s_ashr_i32 s7, s6, 31
	s_lshl_b64 s[2:3], s[6:7], 21
	v_ashrrev_i32_e32 v125, 31, v124
	s_add_u32 s2, s49, s2
	v_lshlrev_b64 v[124:125], 10, v[124:125]
	s_addc_u32 s3, s51, s3
	v_lshl_add_u64 v[124:125], s[2:3], 0, v[124:125]
	v_lshl_add_u64 v[124:125], v[124:125], 0, v[12:13]
	s_mov_b64 s[2:3], 0x4000
	global_store_dwordx4 v[124:125], v[84:87], off sc1
	global_store_dwordx4 v[124:125], v[88:91], off offset:64 sc1
	global_store_dwordx4 v[124:125], v[116:119], off offset:512 sc1
	global_store_dwordx4 v[124:125], v[52:55], off offset:576 sc1
	s_add_i32 s56, s56, s76
	s_mov_b32 s6, s63
	v_lshl_add_u64 v[52:53], v[124:125], 0, s[2:3]
	s_movk_i32 s2, 0x4000
	v_add_co_u32_e32 v54, vcc, s2, v124
	s_mov_b64 s[2:3], 0x8000
	s_nop 0
	v_addc_co_u32_e32 v55, vcc, 0, v125, vcc
	global_store_dwordx4 v[54:55], v[92:95], off sc1
	global_store_dwordx4 v[52:53], v[96:99], off offset:64 sc1
	global_store_dwordx4 v[52:53], v[56:59], off offset:512 sc1
	global_store_dwordx4 v[52:53], v[60:63], off offset:576 sc1
	v_lshl_add_u64 v[52:53], v[124:125], 0, s[2:3]
	s_mov_b32 s2, 0x8000
	v_add_co_u32_e32 v54, vcc, s2, v124
	s_mov_b32 s2, 0xc000
	s_nop 0
	v_addc_co_u32_e32 v55, vcc, 0, v125, vcc
	global_store_dwordx4 v[54:55], v[100:103], off sc1
	global_store_dwordx4 v[52:53], v[104:107], off offset:64 sc1
	global_store_dwordx4 v[52:53], v[64:67], off offset:512 sc1
	global_store_dwordx4 v[52:53], v[68:71], off offset:576 sc1
	v_add_co_u32_e32 v54, vcc, s2, v124
	v_lshl_add_u64 v[52:53], v[124:125], 0, s[12:13]
	s_nop 0
	v_addc_co_u32_e32 v55, vcc, 0, v125, vcc
	global_store_dwordx4 v[54:55], v[108:111], off sc1
	global_store_dwordx4 v[52:53], v[112:115], off offset:64 sc1
	global_store_dwordx4 v[52:53], v[72:75], off offset:512 sc1
	global_store_dwordx4 v[52:53], v[76:79], off offset:576 sc1
	v_add_co_u32_e32 v54, vcc, s59, v124
	v_lshl_add_u64 v[52:53], v[124:125], 0, s[14:15]
	s_nop 0
	v_addc_co_u32_e32 v55, vcc, 0, v125, vcc
	global_store_dwordx4 v[54:55], v[148:151], off sc1
	global_store_dwordx4 v[52:53], v[152:155], off offset:64 sc1
	global_store_dwordx4 v[52:53], v[28:31], off offset:512 sc1
	global_store_dwordx4 v[52:53], v[32:35], off offset:576 sc1
	s_mov_b32 s7, s62
	v_add_co_u32_e32 v30, vcc, s60, v124
	v_lshl_add_u64 v[28:29], v[124:125], 0, s[16:17]
	s_nop 0
	v_addc_co_u32_e32 v31, vcc, 0, v125, vcc
	global_store_dwordx4 v[30:31], v[156:159], off sc1
	global_store_dwordx4 v[28:29], v[160:163], off offset:64 sc1
	global_store_dwordx4 v[28:29], v[44:47], off offset:512 sc1
	global_store_dwordx4 v[28:29], v[48:51], off offset:576 sc1
	v_add_co_u32_e32 v30, vcc, s61, v124
	v_lshl_add_u64 v[28:29], v[124:125], 0, s[18:19]
	s_nop 0
	v_addc_co_u32_e32 v31, vcc, 0, v125, vcc
	global_store_dwordx4 v[30:31], v[164:167], off sc1
	global_store_dwordx4 v[28:29], v[168:171], off offset:64 sc1
	global_store_dwordx4 v[28:29], v[80:83], off offset:512 sc1
	global_store_dwordx4 v[28:29], v[120:123], off offset:576 sc1
	v_add_co_u32_e32 v30, vcc, 0x2c000, v124
	s_mov_b64 s[38:39], s[34:35]
	s_nop 0
	v_addc_co_u32_e32 v31, vcc, 0, v125, vcc
	s_andn2_b64 vcc, exec, s[0:1]
	s_mov_b64 s[36:37], s[30:31]
	v_lshl_add_u64 v[28:29], v[124:125], 0, s[20:21]
	global_store_dwordx4 v[30:31], v[20:23], off sc1
	global_store_dwordx4 v[28:29], v[24:27], off offset:64 sc1
	global_store_dwordx4 v[28:29], v[36:39], off offset:512 sc1
	global_store_dwordx4 v[28:29], v[40:43], off offset:576 sc1
	s_cbranch_vccz .LBB0_368

.LBB0_515:
	s_waitcnt lgkmcnt(3)
	v_mfma_f32_32x32x16_bf16 v[48:63], v[100:103], v[64:67], 0
	s_waitcnt lgkmcnt(2)
	v_mfma_f32_32x32x16_bf16 v[48:63], v[96:99], v[68:71], v[48:63]
	s_waitcnt lgkmcnt(1)
	v_mfma_f32_32x32x16_bf16 v[48:63], v[92:95], v[72:75], v[48:63]
	s_waitcnt lgkmcnt(0)
	v_mfma_f32_32x32x16_bf16 v[48:63], v[88:91], v[76:79], v[48:63]
	s_nop 2
	ds_read_b128 v[32:35], v131 offset:4608
	ds_read_b128 v[88:91], v131 offset:4640
	s_waitcnt lgkmcnt(1)
	v_mfma_f32_32x32x16_bf16 v[32:47], v[32:35], v[64:67], 0
	s_waitcnt lgkmcnt(0)
	v_mfma_f32_32x32x16_bf16 v[32:47], v[88:91], v[68:71], v[32:47]
	ds_read_b128 v[88:91], v131 offset:4672
	s_waitcnt lgkmcnt(0)
	v_mfma_f32_32x32x16_bf16 v[32:47], v[88:91], v[72:75], v[32:47]
	ds_read_b128 v[88:91], v131 offset:4704
	s_waitcnt lgkmcnt(0)
	v_mfma_f32_32x32x16_bf16 v[32:47], v[88:91], v[76:79], v[32:47]
	s_and_b64 vcc, s[66:67], s[0:1]
	v_cndmask_b32_e32 v48, v120, v48, vcc
	s_and_b64 vcc, s[66:67], s[10:11]
	v_cndmask_b32_e32 v49, v120, v49, vcc
	s_and_b64 vcc, s[66:67], s[2:3]
	v_cndmask_b32_e32 v50, v120, v50, vcc
	s_and_b64 vcc, s[66:67], s[4:5]
	v_cndmask_b32_e32 v51, v120, v51, vcc
	s_and_b64 vcc, s[66:67], s[6:7]
	v_cndmask_b32_e32 v52, v120, v52, vcc
	s_and_b64 vcc, s[66:67], s[8:9]
	v_cndmask_b32_e32 v53, v120, v53, vcc
	s_and_b64 vcc, s[66:67], s[14:15]
	v_cndmask_b32_e32 v54, v120, v54, vcc
	s_and_b64 vcc, s[66:67], s[16:17]
	v_cndmask_b32_e32 v55, v120, v55, vcc
	s_and_b64 vcc, s[66:67], s[18:19]
	v_cndmask_b32_e32 v56, v120, v56, vcc
	s_and_b64 vcc, s[66:67], s[20:21]
	v_cndmask_b32_e32 v57, v120, v57, vcc
	s_and_b64 vcc, s[66:67], s[22:23]
	v_cndmask_b32_e32 v58, v120, v58, vcc
	s_and_b64 vcc, s[66:67], s[24:25]
	v_cndmask_b32_e32 v59, v120, v59, vcc
	s_and_b64 vcc, s[66:67], s[26:27]
	v_cndmask_b32_e32 v60, v120, v60, vcc
	s_and_b64 vcc, s[66:67], s[28:29]
	v_cndmask_b32_e32 v61, v120, v61, vcc
	s_and_b64 vcc, s[66:67], s[30:31]
	v_cndmask_b32_e32 v62, v120, v62, vcc
	s_and_b64 vcc, s[66:67], s[34:35]
	v_cndmask_b32_e32 v63, v120, v63, vcc
	s_and_b64 vcc, s[66:67], s[36:37]
	v_cndmask_b32_e32 v32, v120, v32, vcc
	s_and_b64 vcc, s[66:67], s[12:13]
	v_max3_f32 v88, v48, s33, v49
	v_cndmask_b32_e32 v33, v120, v33, vcc
	s_and_b64 vcc, s[66:67], s[38:39]
	v_max3_f32 v88, v88, v50, v51
	v_cndmask_b32_e32 v34, v120, v34, vcc
	s_and_b64 vcc, s[66:67], s[40:41]
	v_max3_f32 v88, v88, v52, v53
	v_cndmask_b32_e32 v35, v120, v35, vcc
	s_and_b64 vcc, s[66:67], s[42:43]
	v_max3_f32 v88, v88, v54, v55
	v_cndmask_b32_e32 v36, v120, v36, vcc
	s_and_b64 vcc, s[66:67], s[44:45]
	v_max3_f32 v88, v88, v56, v57
	v_cndmask_b32_e32 v37, v120, v37, vcc
	s_and_b64 vcc, s[66:67], s[46:47]
	v_max3_f32 v88, v88, v58, v59
	v_cndmask_b32_e32 v38, v120, v38, vcc
	s_and_b64 vcc, s[66:67], s[48:49]
	v_max3_f32 v88, v88, v60, v61
	v_cndmask_b32_e32 v39, v120, v39, vcc
	s_and_b64 vcc, s[66:67], s[50:51]
	v_max3_f32 v88, v88, v62, v63
	v_cndmask_b32_e32 v40, v120, v40, vcc
	s_and_b64 vcc, s[66:67], s[52:53]
	v_max3_f32 v88, v88, v32, v33
	v_cndmask_b32_e32 v41, v120, v41, vcc
	s_and_b64 vcc, s[66:67], s[54:55]
	v_max3_f32 v88, v88, v34, v35
	v_cndmask_b32_e32 v42, v120, v42, vcc
	s_and_b64 vcc, s[66:67], s[56:57]
	v_max3_f32 v88, v88, v36, v37
	v_cndmask_b32_e32 v43, v120, v43, vcc
	s_and_b64 vcc, s[66:67], s[58:59]
	v_max3_f32 v88, v88, v38, v39
	v_cndmask_b32_e32 v44, v120, v44, vcc
	s_and_b64 vcc, s[66:67], s[60:61]
	v_max3_f32 v88, v88, v40, v41
	v_cndmask_b32_e32 v45, v120, v45, vcc
	s_and_b64 vcc, s[66:67], s[62:63]
	v_max3_f32 v88, v88, v42, v43
	v_cndmask_b32_e32 v46, v120, v46, vcc
	s_and_b64 vcc, s[66:67], s[64:65]
	v_max3_f32 v88, v88, v44, v45
	v_cndmask_b32_e32 v47, v120, v47, vcc
	v_max3_f32 v88, v88, v46, v47
	ds_bpermute_b32 v89, v113, v88
	s_waitcnt lgkmcnt(0)
	v_max3_f32 v128, v129, v88, v89
	v_sub_f32_e32 v48, v48, v128
	v_exp_f32_e32 v88, v48
	v_sub_f32_e32 v49, v49, v128
	v_exp_f32_e32 v90, v49
	v_sub_f32_e32 v49, v50, v128
	v_exp_f32_e32 v91, v49
	v_sub_f32_e32 v49, v51, v128
	v_exp_f32_e32 v92, v49
	v_sub_f32_e32 v49, v52, v128
	v_add_f32_e32 v89, 0, v88
	v_exp_f32_e32 v93, v49
	v_sub_f32_e32 v50, v53, v128
	v_add_f32_e32 v49, v90, v89
	v_exp_f32_e32 v89, v50
	v_sub_f32_e32 v50, v54, v128
	v_add_f32_e32 v49, v91, v49
	v_exp_f32_e32 v94, v50
	v_sub_f32_e32 v50, v55, v128
	v_add_f32_e32 v49, v92, v49
	v_exp_f32_e32 v95, v50
	v_sub_f32_e32 v50, v56, v128
	v_add_f32_e32 v49, v93, v49
	v_exp_f32_e32 v96, v50
	v_sub_f32_e32 v50, v57, v128
	v_add_f32_e32 v49, v89, v49
	v_exp_f32_e32 v97, v50
	v_sub_f32_e32 v50, v58, v128
	v_add_f32_e32 v49, v94, v49
	v_exp_f32_e32 v98, v50
	v_sub_f32_e32 v50, v59, v128
	v_add_f32_e32 v49, v95, v49
	v_exp_f32_e32 v99, v50
	v_sub_f32_e32 v50, v60, v128
	v_add_f32_e32 v49, v96, v49
	v_exp_f32_e32 v100, v50
	v_sub_f32_e32 v50, v61, v128
	v_add_f32_e32 v49, v97, v49
	v_exp_f32_e32 v101, v50
	v_sub_f32_e32 v50, v62, v128
	v_add_f32_e32 v49, v98, v49
	v_exp_f32_e32 v102, v50
	v_sub_f32_e32 v50, v63, v128
	v_add_f32_e32 v49, v99, v49
	v_exp_f32_e32 v103, v50
	v_sub_f32_e32 v32, v32, v128
	v_sub_f32_e32 v48, v129, v128
	v_add_f32_e32 v49, v100, v49
	v_exp_f32_e32 v129, v32
	v_sub_f32_e32 v33, v33, v128
	v_add_f32_e32 v32, v101, v49
	v_exp_f32_e32 v131, v33
	v_sub_f32_e32 v33, v34, v128
	v_add_f32_e32 v32, v102, v32
	v_exp_f32_e32 v132, v33
	v_sub_f32_e32 v33, v35, v128
	v_add_f32_e32 v32, v103, v32
	v_exp_f32_e32 v133, v33
	v_sub_f32_e32 v33, v36, v128
	v_add_f32_e32 v32, v129, v32
	v_exp_f32_e32 v134, v33
	v_sub_f32_e32 v33, v37, v128
	v_add_f32_e32 v32, v131, v32
	v_exp_f32_e32 v135, v33
	v_sub_f32_e32 v33, v38, v128
	v_add_f32_e32 v32, v132, v32
	v_exp_f32_e32 v136, v33
	v_sub_f32_e32 v33, v39, v128
	v_add_f32_e32 v32, v133, v32
	v_exp_f32_e32 v137, v33
	v_sub_f32_e32 v33, v40, v128
	v_add_f32_e32 v32, v134, v32
	v_exp_f32_e32 v138, v33
	v_sub_f32_e32 v33, v41, v128
	v_add_f32_e32 v32, v135, v32
	v_exp_f32_e32 v139, v33
	v_sub_f32_e32 v33, v42, v128
	v_add_f32_e32 v32, v136, v32
	v_exp_f32_e32 v140, v33
	v_sub_f32_e32 v33, v43, v128
	v_add_f32_e32 v32, v137, v32
	v_exp_f32_e32 v141, v33
	v_sub_f32_e32 v33, v44, v128
	v_add_f32_e32 v32, v138, v32
	v_exp_f32_e32 v142, v33
	v_add_f32_e32 v32, v139, v32
	v_add_f32_e32 v32, v140, v32
	v_add_f32_e32 v32, v141, v32
	v_add_f32_e32 v33, v142, v32
	v_sub_f32_e32 v32, v45, v128
	v_exp_f32_e32 v143, v32
	v_sub_f32_e32 v32, v46, v128
	v_exp_f32_e32 v144, v32
	v_sub_f32_e32 v32, v47, v128
	v_exp_f32_e32 v145, v32
	v_exp_f32_e32 v32, v48
	v_add_f32_e32 v33, v143, v33
	v_add_f32_e32 v33, v144, v33
	v_add_f32_e32 v130, v145, v33
	v_pk_mul_f32 v[38:39], v[6:7], v[32:33] op_sel_hi:[1,0]
	v_pk_mul_f32 v[36:37], v[4:5], v[32:33] op_sel_hi:[1,0]
	ds_read2_b64 v[4:7], v116 offset1:2
	v_fmac_f32_e32 v130, v117, v32
	v_pk_mul_f32 v[62:63], v[30:31], v[32:33] op_sel_hi:[1,0]
	v_pk_mul_f32 v[60:61], v[28:29], v[32:33] op_sel_hi:[1,0]
	v_pk_mul_f32 v[58:59], v[26:27], v[32:33] op_sel_hi:[1,0]
	v_pk_mul_f32 v[56:57], v[24:25], v[32:33] op_sel_hi:[1,0]
	v_pk_mul_f32 v[54:55], v[22:23], v[32:33] op_sel_hi:[1,0]
	v_pk_mul_f32 v[52:53], v[20:21], v[32:33] op_sel_hi:[1,0]
	v_pk_mul_f32 v[50:51], v[18:19], v[32:33] op_sel_hi:[1,0]
	v_pk_mul_f32 v[48:49], v[16:17], v[32:33] op_sel_hi:[1,0]
	v_pk_mul_f32 v[46:47], v[14:15], v[32:33] op_sel_hi:[1,0]
	v_pk_mul_f32 v[44:45], v[12:13], v[32:33] op_sel_hi:[1,0]
	v_pk_mul_f32 v[42:43], v[10:11], v[32:33] op_sel_hi:[1,0]
	v_pk_mul_f32 v[40:41], v[8:9], v[32:33] op_sel_hi:[1,0]
	v_pk_mul_f32 v[34:35], v[2:3], v[32:33] op_sel_hi:[1,0]
	v_pk_mul_f32 v[32:33], v[0:1], v[32:33] op_sel_hi:[1,0]
	v_cvt_pk_bf16_f32 v0, v88, v90
	v_cvt_pk_bf16_f32 v1, v91, v92
	v_cvt_pk_bf16_f32 v2, v93, v89
	v_cvt_pk_bf16_f32 v3, v94, v95
	ds_read2_b64 v[16:19], v116 offset0:4 offset1:6
	v_cvt_pk_bf16_f32 v8, v96, v97
	s_waitcnt lgkmcnt(1)
	v_mfma_f32_32x32x16_bf16 v[48:63], v[4:7], v[0:3], v[48:63]
	v_cvt_pk_bf16_f32 v9, v98, v99
	v_cvt_pk_bf16_f32 v10, v100, v101
	v_cvt_pk_bf16_f32 v11, v102, v103
	v_cvt_pk_bf16_f32 v12, v129, v131
	v_cvt_pk_bf16_f32 v13, v132, v133
	v_cvt_pk_bf16_f32 v14, v134, v135
	v_cvt_pk_bf16_f32 v15, v136, v137
	s_waitcnt lgkmcnt(0)
	v_mfma_f32_32x32x16_bf16 v[48:63], v[16:19], v[8:11], v[48:63]
	v_cvt_pk_bf16_f32 v4, v138, v139
	v_cvt_pk_bf16_f32 v5, v140, v141
	v_cvt_pk_bf16_f32 v6, v142, v143
	v_cvt_pk_bf16_f32 v7, v144, v145
	ds_read2_b64 v[16:19], v116 offset0:8 offset1:10
	s_waitcnt lgkmcnt(0)
	v_mfma_f32_32x32x16_bf16 v[48:63], v[16:19], v[12:15], v[48:63]
	ds_read2_b64 v[16:19], v116 offset0:12 offset1:14
	s_waitcnt lgkmcnt(0)
	v_mfma_f32_32x32x16_bf16 v[48:63], v[16:19], v[4:7], v[48:63]
	ds_read2_b64 v[16:19], v111 offset0:64 offset1:66
	s_waitcnt lgkmcnt(0)
	v_mfma_f32_32x32x16_bf16 v[32:47], v[16:19], v[0:3], v[32:47]
	ds_read2_b64 v[0:3], v111 offset0:68 offset1:70
	s_waitcnt lgkmcnt(0)
	v_mfma_f32_32x32x16_bf16 v[32:47], v[0:3], v[8:11], v[32:47]
	ds_read2_b64 v[0:3], v111 offset0:72 offset1:74
	s_waitcnt lgkmcnt(0)
	v_mfma_f32_32x32x16_bf16 v[32:47], v[0:3], v[12:15], v[32:47]
	ds_read2_b64 v[0:3], v111 offset0:76 offset1:78
	s_waitcnt lgkmcnt(0)
	v_mfma_f32_32x32x16_bf16 v[32:47], v[0:3], v[4:7], v[32:47]
	s_andn2_b64 vcc, exec, s[68:69]
	s_xor_b32 s73, s73, 1
	s_cbranch_vccz .LBB0_511
	s_branch .LBB0_512
	s_nop 0
	s_nop 0
	s_nop 0
	s_nop 0
	s_nop 0
	s_nop 0
	s_nop 0
	s_nop 0
	s_nop 0
	s_nop 0
	s_nop 0
	s_nop 0
	s_nop 0
	s_nop 0
	s_nop 0
	s_nop 0
	s_nop 0
	s_nop 0
	s_nop 0
	s_nop 0
	s_nop 0
	s_nop 0
	s_nop 0
	s_nop 0
	s_nop 0
	s_nop 0
	s_nop 0
	s_nop 0
	s_nop 0
	s_nop 0
	s_nop 0
	s_nop 0
	s_nop 0
	s_nop 0
	s_nop 0
	s_nop 0
	s_nop 0
	s_nop 0
	s_nop 0
	s_nop 0
	s_nop 0
	s_nop 0
	s_nop 0
	s_nop 0
	s_nop 0
	s_nop 0
	s_nop 0
	s_nop 0
	s_nop 0
	s_nop 0
	s_nop 0
	s_nop 0
	s_nop 0
	s_nop 0
	s_nop 0
	s_nop 0
	s_nop 0
	s_nop 0
	s_nop 0
	s_nop 0
	s_nop 0
	s_nop 0
	s_nop 0
	s_nop 0
	s_nop 0
	s_nop 0
	s_nop 0
	s_nop 0
	s_nop 0
	s_nop 0
	s_nop 0
	s_nop 0
	s_nop 0
	s_nop 0
	s_nop 0
	s_nop 0
	s_nop 0
	s_nop 0
	s_nop 0
	s_nop 0
	s_nop 0
	s_nop 0
	s_nop 0
	s_nop 0
	s_nop 0
	s_nop 0
	s_nop 0
	s_nop 0
	s_nop 0
	s_nop 0
	s_nop 0
	s_nop 0
	s_nop 0
	s_nop 0
	s_nop 0
	s_nop 0
	s_nop 0
	s_nop 0
	s_nop 0
	s_nop 0
	s_nop 0
	s_nop 0
	s_nop 0
	s_nop 0
	s_nop 0
	s_nop 0
	s_nop 0
	s_nop 0
	s_nop 0
	s_nop 0
	s_nop 0
	s_nop 0
	s_nop 0
	s_nop 0
	s_nop 0
	s_nop 0
	s_nop 0
	s_nop 0
	s_nop 0
	s_nop 0
	s_nop 0
	s_nop 0
	s_nop 0
	s_nop 0
	s_nop 0
	s_nop 0
	s_nop 0
	s_nop 0
	s_nop 0
	s_nop 0
	s_nop 0
	s_nop 0
	s_nop 0
	s_nop 0
	s_nop 0
	s_nop 0
	s_nop 0
	s_nop 0
	s_nop 0
	s_nop 0
	s_nop 0
	s_nop 0
	s_nop 0
	s_nop 0
	s_nop 0
	s_nop 0
	s_nop 0
	s_nop 0
	s_nop 0
	s_nop 0
	s_nop 0
	s_nop 0
	s_nop 0
	s_nop 0
	s_nop 0
	s_nop 0
	s_nop 0
	s_nop 0
	s_nop 0
	s_nop 0
	s_nop 0
	s_nop 0
	s_nop 0
	s_nop 0
	s_nop 0
	s_nop 0
	s_nop 0
	s_nop 0

.LBB0_577:
	s_ashr_i32 s21, s34, 31
	s_lshr_b32 s21, s21, 29
	v_lshl_add_u32 v156, s34, 8, v158
	v_lshl_or_b32 v164, s58, 8, v160
	s_add_i32 s21, s34, s21
	s_ashr_i32 s21, s21, 3
	v_ashrrev_i32_e32 v165, 31, v164
	s_mul_hi_i32 s23, s21, 0x6000
	s_mulk_i32 s21, 0x6000
	s_add_u32 s36, s50, s21
	v_lshlrev_b32_e32 v157, 12, v156
	s_addc_u32 s37, s51, s23
	v_lshl_add_u32 v157, v164, 2, v157
	v_lshl_add_u64 v[128:129], v[164:165], 2, s[36:37]
	s_nop 0
	global_load_dwordx4 v[140:143], v[128:129], off
	global_load_dwordx4 v[136:139], v[128:129], off offset:64
	global_load_dwordx4 v[132:135], v[128:129], off offset:512
	s_nop 0
	global_load_dwordx4 v[128:131], v[128:129], off offset:576
	s_andn2_b64 vcc, exec, s[10:11]
	s_mov_b64 s[10:11], -1
	v_add_u32_e32 v164, 0x10000, v157
	v_add_u32_e32 v165, 0x20000, v157
	v_add_u32_e32 v166, 0x30000, v157
	v_add_u32_e32 v167, 0x80000, v157
	v_add_u32_e32 v168, 0x90000, v157
	v_add_u32_e32 v169, 0xa0000, v157
	v_add_u32_e32 v170, 0xb0000, v157
	global_load_dwordx4 v[172:175], v157, s[0:1]
	global_load_dwordx4 v[176:179], v157, s[0:1] offset:64
	global_load_dwordx4 v[180:183], v157, s[0:1] offset:512
	global_load_dwordx4 v[184:187], v157, s[0:1] offset:576
	global_load_dwordx4 v[188:191], v164, s[0:1]
	global_load_dwordx4 v[192:195], v164, s[0:1] offset:64
	global_load_dwordx4 v[196:199], v164, s[0:1] offset:512
	global_load_dwordx4 v[200:203], v164, s[0:1] offset:576
	global_load_dwordx4 v[204:207], v165, s[0:1]
	global_load_dwordx4 v[208:211], v165, s[0:1] offset:64
	global_load_dwordx4 v[212:215], v165, s[0:1] offset:512
	global_load_dwordx4 v[216:219], v165, s[0:1] offset:576
	s_waitcnt vmcnt(11)
	v_pk_fma_f32 v[124:125], v[124:125], v[140:141], v[172:173]
	v_pk_fma_f32 v[126:127], v[126:127], v[142:143], v[174:175]
	global_store_dwordx4 v157, v[124:127], s[2:3] sc1
	global_load_dwordx4 v[172:175], v166, s[0:1]
	s_waitcnt vmcnt(12)
	v_pk_fma_f32 v[120:121], v[120:121], v[136:137], v[176:177]
	v_pk_fma_f32 v[122:123], v[122:123], v[138:139], v[178:179]
	global_store_dwordx4 v157, v[120:123], s[2:3] offset:64 sc1
	global_load_dwordx4 v[176:179], v166, s[0:1] offset:64
	s_waitcnt vmcnt(13)
	v_pk_fma_f32 v[116:117], v[116:117], v[132:133], v[180:181]
	v_pk_fma_f32 v[118:119], v[118:119], v[134:135], v[182:183]
	global_store_dwordx4 v157, v[116:119], s[2:3] offset:512 sc1
	global_load_dwordx4 v[180:183], v166, s[0:1] offset:512
	s_waitcnt vmcnt(14)
	v_pk_fma_f32 v[104:105], v[104:105], v[128:129], v[184:185]
	v_pk_fma_f32 v[106:107], v[106:107], v[130:131], v[186:187]
	global_store_dwordx4 v157, v[104:107], s[2:3] offset:576 sc1
	global_load_dwordx4 v[184:187], v166, s[0:1] offset:576
	s_waitcnt vmcnt(15)
	v_pk_fma_f32 v[112:113], v[112:113], v[140:141], v[188:189]
	v_pk_fma_f32 v[114:115], v[114:115], v[142:143], v[190:191]
	global_store_dwordx4 v164, v[112:115], s[2:3] sc1
	global_load_dwordx4 v[188:191], v167, s[0:1]
	s_waitcnt vmcnt(16)
	v_pk_fma_f32 v[108:109], v[108:109], v[136:137], v[192:193]
	v_pk_fma_f32 v[110:111], v[110:111], v[138:139], v[194:195]
	global_store_dwordx4 v164, v[108:111], s[2:3] offset:64 sc1
	global_load_dwordx4 v[192:195], v167, s[0:1] offset:64
	s_waitcnt vmcnt(17)
	v_pk_fma_f32 v[100:101], v[100:101], v[132:133], v[196:197]
	v_pk_fma_f32 v[102:103], v[102:103], v[134:135], v[198:199]
	global_store_dwordx4 v164, v[100:103], s[2:3] offset:512 sc1
	global_load_dwordx4 v[196:199], v167, s[0:1] offset:512
	s_waitcnt vmcnt(18)
	v_pk_fma_f32 v[88:89], v[88:89], v[128:129], v[200:201]
	v_pk_fma_f32 v[90:91], v[90:91], v[130:131], v[202:203]
	global_store_dwordx4 v164, v[88:91], s[2:3] offset:576 sc1
	global_load_dwordx4 v[200:203], v167, s[0:1] offset:576
	s_waitcnt vmcnt(19)
	v_pk_fma_f32 v[96:97], v[96:97], v[140:141], v[204:205]
	v_pk_fma_f32 v[98:99], v[98:99], v[142:143], v[206:207]
	global_store_dwordx4 v165, v[96:99], s[2:3] sc1
	global_load_dwordx4 v[204:207], v168, s[0:1]
	s_waitcnt vmcnt(20)
	v_pk_fma_f32 v[92:93], v[92:93], v[136:137], v[208:209]
	v_pk_fma_f32 v[94:95], v[94:95], v[138:139], v[210:211]
	global_store_dwordx4 v165, v[92:95], s[2:3] offset:64 sc1
	global_load_dwordx4 v[208:211], v168, s[0:1] offset:64
	s_waitcnt vmcnt(21)
	v_pk_fma_f32 v[84:85], v[84:85], v[132:133], v[212:213]
	v_pk_fma_f32 v[86:87], v[86:87], v[134:135], v[214:215]
	global_store_dwordx4 v165, v[84:87], s[2:3] offset:512 sc1
	global_load_dwordx4 v[212:215], v168, s[0:1] offset:512
	s_waitcnt vmcnt(22)
	v_pk_fma_f32 v[72:73], v[72:73], v[128:129], v[216:217]
	v_pk_fma_f32 v[74:75], v[74:75], v[130:131], v[218:219]
	global_store_dwordx4 v165, v[72:75], s[2:3] offset:576 sc1
	global_load_dwordx4 v[216:219], v168, s[0:1] offset:576
	s_waitcnt vmcnt(22)
	v_pk_fma_f32 v[80:81], v[80:81], v[140:141], v[172:173]
	v_pk_fma_f32 v[82:83], v[82:83], v[142:143], v[174:175]
	global_store_dwordx4 v166, v[80:83], s[2:3] sc1
	global_load_dwordx4 v[172:175], v169, s[0:1]
	s_waitcnt vmcnt(22)
	v_pk_fma_f32 v[76:77], v[76:77], v[136:137], v[176:177]
	v_pk_fma_f32 v[78:79], v[78:79], v[138:139], v[178:179]
	global_store_dwordx4 v166, v[76:79], s[2:3] offset:64 sc1
	global_load_dwordx4 v[176:179], v169, s[0:1] offset:64
	s_waitcnt vmcnt(22)
	v_pk_fma_f32 v[68:69], v[68:69], v[132:133], v[180:181]
	v_pk_fma_f32 v[70:71], v[70:71], v[134:135], v[182:183]
	global_store_dwordx4 v166, v[68:71], s[2:3] offset:512 sc1
	global_load_dwordx4 v[180:183], v169, s[0:1] offset:512
	s_waitcnt vmcnt(22)
	v_pk_fma_f32 v[64:65], v[64:65], v[128:129], v[184:185]
	v_pk_fma_f32 v[66:67], v[66:67], v[130:131], v[186:187]
	global_store_dwordx4 v166, v[64:67], s[2:3] offset:576 sc1
	global_load_dwordx4 v[184:187], v169, s[0:1] offset:576
	s_waitcnt vmcnt(22)
	v_pk_fma_f32 v[60:61], v[60:61], v[140:141], v[188:189]
	v_pk_fma_f32 v[62:63], v[62:63], v[142:143], v[190:191]
	global_store_dwordx4 v167, v[60:63], s[2:3] sc1
	global_load_dwordx4 v[188:191], v170, s[0:1]
	s_waitcnt vmcnt(22)
	v_pk_fma_f32 v[56:57], v[56:57], v[136:137], v[192:193]
	v_pk_fma_f32 v[58:59], v[58:59], v[138:139], v[194:195]
	global_store_dwordx4 v167, v[56:59], s[2:3] offset:64 sc1
	global_load_dwordx4 v[192:195], v170, s[0:1] offset:64
	s_waitcnt vmcnt(22)
	v_pk_fma_f32 v[52:53], v[52:53], v[132:133], v[196:197]
	v_pk_fma_f32 v[54:55], v[54:55], v[134:135], v[198:199]
	global_store_dwordx4 v167, v[52:55], s[2:3] offset:512 sc1
	global_load_dwordx4 v[196:199], v170, s[0:1] offset:512
	s_waitcnt vmcnt(22)
	v_pk_fma_f32 v[40:41], v[40:41], v[128:129], v[200:201]
	v_pk_fma_f32 v[42:43], v[42:43], v[130:131], v[202:203]
	global_store_dwordx4 v167, v[40:43], s[2:3] offset:576 sc1
	global_load_dwordx4 v[200:203], v170, s[0:1] offset:576
	s_waitcnt vmcnt(22)
	v_pk_fma_f32 v[48:49], v[48:49], v[140:141], v[204:205]
	v_pk_fma_f32 v[50:51], v[50:51], v[142:143], v[206:207]
	global_store_dwordx4 v168, v[48:51], s[2:3] sc1
	s_waitcnt vmcnt(21)
	v_pk_fma_f32 v[44:45], v[44:45], v[136:137], v[208:209]
	v_pk_fma_f32 v[46:47], v[46:47], v[138:139], v[210:211]
	global_store_dwordx4 v168, v[44:47], s[2:3] offset:64 sc1
	s_waitcnt vmcnt(20)
	v_pk_fma_f32 v[36:37], v[36:37], v[132:133], v[212:213]
	v_pk_fma_f32 v[38:39], v[38:39], v[134:135], v[214:215]
	global_store_dwordx4 v168, v[36:39], s[2:3] offset:512 sc1
	s_waitcnt vmcnt(19)
	v_pk_fma_f32 v[24:25], v[24:25], v[128:129], v[216:217]
	v_pk_fma_f32 v[26:27], v[26:27], v[130:131], v[218:219]
	global_store_dwordx4 v168, v[24:27], s[2:3] offset:576 sc1
	s_waitcnt vmcnt(18)
	v_pk_fma_f32 v[32:33], v[32:33], v[140:141], v[172:173]
	v_pk_fma_f32 v[34:35], v[34:35], v[142:143], v[174:175]
	global_store_dwordx4 v169, v[32:35], s[2:3] sc1
	s_waitcnt vmcnt(17)
	v_pk_fma_f32 v[28:29], v[28:29], v[136:137], v[176:177]
	v_pk_fma_f32 v[30:31], v[30:31], v[138:139], v[178:179]
	global_store_dwordx4 v169, v[28:31], s[2:3] offset:64 sc1
	s_waitcnt vmcnt(16)
	v_pk_fma_f32 v[20:21], v[20:21], v[132:133], v[180:181]
	v_pk_fma_f32 v[22:23], v[22:23], v[134:135], v[182:183]
	global_store_dwordx4 v169, v[20:23], s[2:3] offset:512 sc1
	s_waitcnt vmcnt(15)
	v_pk_fma_f32 v[8:9], v[8:9], v[128:129], v[184:185]
	v_pk_fma_f32 v[10:11], v[10:11], v[130:131], v[186:187]
	global_store_dwordx4 v169, v[8:11], s[2:3] offset:576 sc1
	s_waitcnt vmcnt(14)
	v_pk_fma_f32 v[16:17], v[16:17], v[140:141], v[188:189]
	v_pk_fma_f32 v[18:19], v[18:19], v[142:143], v[190:191]
	global_store_dwordx4 v170, v[16:19], s[2:3] sc1
	s_waitcnt vmcnt(13)
	v_pk_fma_f32 v[12:13], v[12:13], v[136:137], v[192:193]
	v_pk_fma_f32 v[14:15], v[14:15], v[138:139], v[194:195]
	global_store_dwordx4 v170, v[12:15], s[2:3] offset:64 sc1
	s_waitcnt vmcnt(12)
	v_pk_fma_f32 v[4:5], v[4:5], v[132:133], v[196:197]
	v_pk_fma_f32 v[6:7], v[6:7], v[134:135], v[198:199]
	global_store_dwordx4 v170, v[4:7], s[2:3] offset:512 sc1
	s_waitcnt vmcnt(11)
	v_pk_fma_f32 v[0:1], v[0:1], v[128:129], v[200:201]
	v_pk_fma_f32 v[2:3], v[2:3], v[130:131], v[202:203]
	global_store_dwordx4 v170, v[0:3], s[2:3] offset:576 sc1
	s_cbranch_vccnz .LBB0_566
	s_andn2_b64 vcc, exec, s[4:5]
	s_cbranch_vccnz .LBB0_565
	s_barrier
	s_branch .LBB0_565

.LBB0_719:
	s_or_b64 exec, exec, s[54:55]
	s_waitcnt lgkmcnt(1)
	v_mov_b32_dpp v107, v100 row_ror:2 row_mask:0xf bank_mask:0xf
	v_mov_b32_dpp v106, v100 row_ror:1 row_mask:0xf bank_mask:0xf
	v_mov_b32_dpp v107, v92 row_shr:2 row_mask:0xf bank_mask:0xf
	v_mov_b32_dpp v106, v92 row_shr:1 row_mask:0xf bank_mask:0xf
	v_fma_f32 v107, v68, v107, v60
	v_fmac_f32_e32 v107, v72, v106
	v_fmac_f32_e32 v107, v92, v76
	v_mul_f32_e32 v106, 0xbfb8aa3b, v107
	v_exp_f32_e32 v106, v106
	s_waitcnt lgkmcnt(0)
	v_mov_b32_dpp v100, v96 row_ror:1 row_mask:0xf bank_mask:0xf
	v_mov_b32_dpp v108, v96 row_ror:2 row_mask:0xf bank_mask:0xf
	v_mov_b32_e32 v129, 0
	v_add_f32_e32 v96, 1.0, v106
	v_rcp_f32_e32 v96, v96
	v_mov_b32_dpp v108, v88 row_shr:2 row_mask:0xf bank_mask:0xf
	v_mov_b32_dpp v100, v88 row_shr:1 row_mask:0xf bank_mask:0xf
	v_fma_f32 v106, v48, v108, v64
	v_fmac_f32_e32 v106, v52, v100
	v_fmac_f32_e32 v106, v88, v56
	v_mul_f32_e32 v96, v107, v96
	v_mul_f32_e32 v96, v106, v96
	v_mov_b32_dpp v106, v101 row_ror:2 row_mask:0xf bank_mask:0xf
	v_mov_b32_dpp v100, v101 row_ror:1 row_mask:0xf bank_mask:0xf
	v_mov_b32_dpp v106, v93 row_shr:2 row_mask:0xf bank_mask:0xf
	v_mov_b32_dpp v100, v93 row_shr:1 row_mask:0xf bank_mask:0xf
	v_fma_f32 v106, v69, v106, v61
	v_fmac_f32_e32 v106, v73, v100
	v_fmac_f32_e32 v106, v93, v77
	v_mul_f32_e32 v100, 0xbfb8aa3b, v106
	v_exp_f32_e32 v100, v100
	v_mov_b32_dpp v101, v97 row_ror:1 row_mask:0xf bank_mask:0xf
	v_mov_b32_dpp v107, v97 row_ror:2 row_mask:0xf bank_mask:0xf
	v_mov_b32_e32 v130, 0
	v_add_f32_e32 v97, 1.0, v100
	v_rcp_f32_e32 v97, v97
	v_mov_b32_dpp v107, v89 row_shr:2 row_mask:0xf bank_mask:0xf
	v_mov_b32_dpp v101, v89 row_shr:1 row_mask:0xf bank_mask:0xf
	v_fma_f32 v100, v49, v107, v65
	v_fmac_f32_e32 v100, v53, v101
	v_fmac_f32_e32 v100, v89, v57
	v_mul_f32_e32 v97, v106, v97
	v_mul_f32_e32 v97, v100, v97
	v_mov_b32_dpp v101, v102 row_ror:2 row_mask:0xf bank_mask:0xf
	v_mov_b32_dpp v100, v102 row_ror:1 row_mask:0xf bank_mask:0xf
	v_mov_b32_dpp v101, v94 row_shr:2 row_mask:0xf bank_mask:0xf
	v_fma_f32 v101, v70, v101, v62
	v_mov_b32_dpp v100, v94 row_shr:1 row_mask:0xf bank_mask:0xf
	v_fmac_f32_e32 v101, v74, v100
	v_fmac_f32_e32 v101, v94, v78
	v_mul_f32_e32 v100, 0xbfb8aa3b, v101
	v_exp_f32_e32 v100, v100
	v_mov_b32_dpp v106, v98 row_ror:2 row_mask:0xf bank_mask:0xf
	v_cvt_pk_bf16_f32 v146, v96, v97
	v_mov_b32_dpp v102, v98 row_ror:1 row_mask:0xf bank_mask:0xf
	v_add_f32_e32 v98, 1.0, v100
	v_rcp_f32_e32 v98, v98
	v_mov_b32_dpp v106, v90 row_shr:2 row_mask:0xf bank_mask:0xf
	v_mov_b32_dpp v102, v90 row_shr:1 row_mask:0xf bank_mask:0xf
	v_fma_f32 v100, v50, v106, v66
	v_fmac_f32_e32 v100, v54, v102
	v_fmac_f32_e32 v100, v90, v58
	v_mul_f32_e32 v98, v101, v98
	v_mul_f32_e32 v98, v100, v98
	v_mov_b32_dpp v101, v103 row_ror:2 row_mask:0xf bank_mask:0xf
	v_mov_b32_dpp v100, v103 row_ror:1 row_mask:0xf bank_mask:0xf
	v_mov_b32_dpp v101, v95 row_shr:2 row_mask:0xf bank_mask:0xf
	v_fma_f32 v101, v71, v101, v63
	v_mov_b32_dpp v100, v95 row_shr:1 row_mask:0xf bank_mask:0xf
	v_fmac_f32_e32 v101, v75, v100
	v_fmac_f32_e32 v101, v95, v79
	v_mul_f32_e32 v100, 0xbfb8aa3b, v101
	v_exp_f32_e32 v100, v100
	v_mov_b32_dpp v102, v99 row_ror:1 row_mask:0xf bank_mask:0xf
	v_mov_b32_dpp v103, v99 row_ror:2 row_mask:0xf bank_mask:0xf
	v_add_f32_e32 v99, 1.0, v100
	v_rcp_f32_e32 v99, v99
	v_mov_b32_dpp v103, v91 row_shr:2 row_mask:0xf bank_mask:0xf
	v_mov_b32_dpp v102, v91 row_shr:1 row_mask:0xf bank_mask:0xf
	v_fma_f32 v100, v51, v103, v67
	v_fmac_f32_e32 v100, v55, v102
	v_fmac_f32_e32 v100, v91, v59
	v_mul_f32_e32 v99, v101, v99
	v_mul_f32_e32 v99, v100, v99
	v_cvt_pk_bf16_f32 v147, v98, v99
	v_mov_b32_e32 v144, v244
	v_mov_b32_e32 v145, v245
	global_store_dwordx4 v[196:197], v[144:147], off sc1
	v_mov_b32_dpp v97, v92 row_ror:2 row_mask:0xf bank_mask:0xf
	v_mov_b32_dpp v96, v92 row_ror:1 row_mask:0xf bank_mask:0xf
	v_mov_b32_dpp v97, v84 row_shr:2 row_mask:0xf bank_mask:0xf
	v_fma_f32 v97, v68, v97, v60
	v_mov_b32_dpp v96, v84 row_shr:1 row_mask:0xf bank_mask:0xf
	v_fmac_f32_e32 v97, v72, v96
	v_fmac_f32_e32 v97, v84, v76
	v_mul_f32_e32 v96, 0xbfb8aa3b, v97
	v_exp_f32_e32 v96, v96
	v_mov_b32_dpp v98, v88 row_ror:2 row_mask:0xf bank_mask:0xf
	v_mov_b32_e32 v131, 0
	v_mov_b32_dpp v92, v88 row_ror:1 row_mask:0xf bank_mask:0xf
	v_add_f32_e32 v88, 1.0, v96
	v_rcp_f32_e32 v88, v88
	v_mov_b32_dpp v98, v80 row_shr:2 row_mask:0xf bank_mask:0xf
	v_mov_b32_dpp v92, v80 row_shr:1 row_mask:0xf bank_mask:0xf
	v_fma_f32 v96, v48, v98, v64
	v_fmac_f32_e32 v96, v52, v92
	v_fmac_f32_e32 v96, v80, v56
	v_mul_f32_e32 v88, v97, v88
	v_mul_f32_e32 v88, v96, v88
	v_mov_b32_dpp v96, v93 row_ror:2 row_mask:0xf bank_mask:0xf
	v_mov_b32_dpp v92, v93 row_ror:1 row_mask:0xf bank_mask:0xf
	v_mov_b32_dpp v96, v85 row_shr:2 row_mask:0xf bank_mask:0xf
	v_mov_b32_dpp v92, v85 row_shr:1 row_mask:0xf bank_mask:0xf
	v_fma_f32 v96, v69, v96, v61
	v_fmac_f32_e32 v96, v73, v92
	v_fmac_f32_e32 v96, v85, v77
	v_mul_f32_e32 v92, 0xbfb8aa3b, v96
	v_exp_f32_e32 v92, v92
	v_mov_b32_dpp v93, v89 row_ror:1 row_mask:0xf bank_mask:0xf
	v_mov_b32_dpp v97, v89 row_ror:2 row_mask:0xf bank_mask:0xf
	v_add_f32_e32 v89, 1.0, v92
	v_rcp_f32_e32 v89, v89
	v_mov_b32_dpp v97, v81 row_shr:2 row_mask:0xf bank_mask:0xf
	v_mov_b32_dpp v93, v81 row_shr:1 row_mask:0xf bank_mask:0xf
	v_fma_f32 v92, v49, v97, v65
	v_fmac_f32_e32 v92, v53, v93
	v_fmac_f32_e32 v92, v81, v57
	v_mul_f32_e32 v89, v96, v89
	v_mul_f32_e32 v89, v92, v89
	v_mov_b32_dpp v93, v94 row_ror:2 row_mask:0xf bank_mask:0xf
	v_mov_b32_dpp v92, v94 row_ror:1 row_mask:0xf bank_mask:0xf
	v_mov_b32_dpp v93, v86 row_shr:2 row_mask:0xf bank_mask:0xf
	v_fma_f32 v93, v70, v93, v62
	v_mov_b32_dpp v92, v86 row_shr:1 row_mask:0xf bank_mask:0xf
	v_fmac_f32_e32 v93, v74, v92
	v_fmac_f32_e32 v93, v86, v78
	v_mul_f32_e32 v92, 0xbfb8aa3b, v93
	v_exp_f32_e32 v92, v92
	v_mov_b32_dpp v96, v90 row_ror:2 row_mask:0xf bank_mask:0xf
	v_cvt_pk_bf16_f32 v146, v88, v89
	v_mov_b32_dpp v94, v90 row_ror:1 row_mask:0xf bank_mask:0xf
	v_add_f32_e32 v90, 1.0, v92
	v_rcp_f32_e32 v90, v90
	v_mov_b32_dpp v96, v82 row_shr:2 row_mask:0xf bank_mask:0xf
	v_mov_b32_dpp v94, v82 row_shr:1 row_mask:0xf bank_mask:0xf
	v_fma_f32 v92, v50, v96, v66
	v_fmac_f32_e32 v92, v54, v94
	v_fmac_f32_e32 v92, v82, v58
	v_mul_f32_e32 v90, v93, v90
	v_mul_f32_e32 v90, v92, v90
	v_mov_b32_dpp v93, v95 row_ror:2 row_mask:0xf bank_mask:0xf
	v_mov_b32_dpp v92, v95 row_ror:1 row_mask:0xf bank_mask:0xf
	v_mov_b32_dpp v93, v87 row_shr:2 row_mask:0xf bank_mask:0xf
	v_fma_f32 v93, v71, v93, v63
	v_mov_b32_dpp v92, v87 row_shr:1 row_mask:0xf bank_mask:0xf
	v_fmac_f32_e32 v93, v75, v92
	v_fmac_f32_e32 v93, v87, v79
	v_mul_f32_e32 v92, 0xbfb8aa3b, v93
	v_exp_f32_e32 v92, v92
	v_mov_b32_dpp v94, v91 row_ror:1 row_mask:0xf bank_mask:0xf
	v_mov_b32_dpp v95, v91 row_ror:2 row_mask:0xf bank_mask:0xf
	v_add_f32_e32 v91, 1.0, v92
	v_rcp_f32_e32 v91, v91
	v_mov_b32_dpp v95, v83 row_shr:2 row_mask:0xf bank_mask:0xf
	v_mov_b32_dpp v94, v83 row_shr:1 row_mask:0xf bank_mask:0xf
	v_fma_f32 v92, v51, v95, v67
	v_fmac_f32_e32 v92, v55, v94
	v_fmac_f32_e32 v92, v83, v59
	v_mul_f32_e32 v91, v93, v91
	v_mul_f32_e32 v91, v92, v91
	v_cvt_pk_bf16_f32 v147, v90, v91
	v_mov_b32_e32 v144, v242
	v_mov_b32_e32 v145, v243
	global_store_dwordx4 v[184:185], v[144:147], off sc1
	v_mov_b32_dpp v89, v84 row_ror:2 row_mask:0xf bank_mask:0xf
	v_mov_b32_dpp v88, v84 row_ror:1 row_mask:0xf bank_mask:0xf
	v_mov_b32_dpp v89, v44 row_shr:2 row_mask:0xf bank_mask:0xf
	v_fma_f32 v89, v68, v89, v60
	v_mov_b32_dpp v88, v44 row_shr:1 row_mask:0xf bank_mask:0xf
	v_fmac_f32_e32 v89, v72, v88
	v_fmac_f32_e32 v89, v44, v76
	v_mul_f32_e32 v88, 0xbfb8aa3b, v89
	v_exp_f32_e32 v88, v88
	v_mov_b32_dpp v90, v80 row_ror:2 row_mask:0xf bank_mask:0xf
	s_nop 0
	v_mov_b32_dpp v84, v80 row_ror:1 row_mask:0xf bank_mask:0xf
	v_add_f32_e32 v80, 1.0, v88
	v_rcp_f32_e32 v80, v80
	v_mov_b32_dpp v90, v36 row_shr:2 row_mask:0xf bank_mask:0xf
	v_mov_b32_dpp v84, v36 row_shr:1 row_mask:0xf bank_mask:0xf
	v_fma_f32 v88, v48, v90, v64
	v_fmac_f32_e32 v88, v52, v84
	v_fmac_f32_e32 v88, v36, v56
	v_mul_f32_e32 v80, v89, v80
	v_mul_f32_e32 v80, v88, v80
	v_mov_b32_dpp v88, v85 row_ror:2 row_mask:0xf bank_mask:0xf
	v_mov_b32_dpp v84, v85 row_ror:1 row_mask:0xf bank_mask:0xf
	v_mov_b32_dpp v88, v45 row_shr:2 row_mask:0xf bank_mask:0xf
	v_mov_b32_dpp v84, v45 row_shr:1 row_mask:0xf bank_mask:0xf
	v_fma_f32 v88, v69, v88, v61
	v_fmac_f32_e32 v88, v73, v84
	v_fmac_f32_e32 v88, v45, v77
	v_mul_f32_e32 v84, 0xbfb8aa3b, v88
	v_exp_f32_e32 v84, v84
	v_mov_b32_dpp v85, v81 row_ror:1 row_mask:0xf bank_mask:0xf
	v_mov_b32_dpp v89, v81 row_ror:2 row_mask:0xf bank_mask:0xf
	v_add_f32_e32 v81, 1.0, v84
	v_rcp_f32_e32 v81, v81
	v_mov_b32_dpp v89, v37 row_shr:2 row_mask:0xf bank_mask:0xf
	v_mov_b32_dpp v85, v37 row_shr:1 row_mask:0xf bank_mask:0xf
	v_fma_f32 v84, v49, v89, v65
	v_fmac_f32_e32 v84, v53, v85
	v_fmac_f32_e32 v84, v37, v57
	v_mul_f32_e32 v81, v88, v81
	v_mul_f32_e32 v81, v84, v81
	v_mov_b32_dpp v85, v86 row_ror:2 row_mask:0xf bank_mask:0xf
	v_mov_b32_dpp v84, v86 row_ror:1 row_mask:0xf bank_mask:0xf
	v_mov_b32_dpp v85, v46 row_shr:2 row_mask:0xf bank_mask:0xf
	v_fma_f32 v85, v70, v85, v62
	v_mov_b32_dpp v84, v46 row_shr:1 row_mask:0xf bank_mask:0xf
	v_fmac_f32_e32 v85, v74, v84
	v_fmac_f32_e32 v85, v46, v78
	v_mul_f32_e32 v84, 0xbfb8aa3b, v85
	v_exp_f32_e32 v84, v84
	v_mov_b32_dpp v88, v82 row_ror:2 row_mask:0xf bank_mask:0xf
	v_cvt_pk_bf16_f32 v146, v80, v81
	v_mov_b32_dpp v86, v82 row_ror:1 row_mask:0xf bank_mask:0xf
	v_add_f32_e32 v82, 1.0, v84
	v_rcp_f32_e32 v82, v82
	v_mov_b32_dpp v88, v38 row_shr:2 row_mask:0xf bank_mask:0xf
	v_mov_b32_dpp v86, v38 row_shr:1 row_mask:0xf bank_mask:0xf
	v_fma_f32 v84, v50, v88, v66
	v_fmac_f32_e32 v84, v54, v86
	v_fmac_f32_e32 v84, v38, v58
	v_mul_f32_e32 v82, v85, v82
	v_mul_f32_e32 v82, v84, v82
	v_mov_b32_dpp v85, v87 row_ror:2 row_mask:0xf bank_mask:0xf
	v_mov_b32_dpp v84, v87 row_ror:1 row_mask:0xf bank_mask:0xf
	v_mov_b32_dpp v85, v47 row_shr:2 row_mask:0xf bank_mask:0xf
	v_fma_f32 v85, v71, v85, v63
	v_mov_b32_dpp v84, v47 row_shr:1 row_mask:0xf bank_mask:0xf
	v_fmac_f32_e32 v85, v75, v84
	v_fmac_f32_e32 v85, v47, v79
	v_mul_f32_e32 v84, 0xbfb8aa3b, v85
	v_exp_f32_e32 v84, v84
	v_mov_b32_dpp v86, v83 row_ror:1 row_mask:0xf bank_mask:0xf
	v_mov_b32_dpp v87, v83 row_ror:2 row_mask:0xf bank_mask:0xf
	v_add_f32_e32 v83, 1.0, v84
	v_rcp_f32_e32 v83, v83
	v_mov_b32_dpp v87, v39 row_shr:2 row_mask:0xf bank_mask:0xf
	v_mov_b32_dpp v86, v39 row_shr:1 row_mask:0xf bank_mask:0xf
	v_fma_f32 v84, v51, v87, v67
	v_fmac_f32_e32 v84, v55, v86
	v_fmac_f32_e32 v84, v39, v59
	v_mul_f32_e32 v83, v85, v83
	v_mul_f32_e32 v83, v84, v83
	v_cvt_pk_bf16_f32 v147, v82, v83
	v_mov_b32_e32 v144, v200
	v_mov_b32_e32 v145, v201
	global_store_dwordx4 v[176:177], v[144:147], off sc1
	v_mov_b32_dpp v81, v44 row_ror:2 row_mask:0xf bank_mask:0xf
	s_nop 0
	v_mov_b32_dpp v80, v44 row_ror:1 row_mask:0xf bank_mask:0xf
	v_mov_b32_dpp v81, v40 row_shr:2 row_mask:0xf bank_mask:0xf
	v_fma_f32 v81, v68, v81, v60
	v_mov_b32_dpp v80, v40 row_shr:1 row_mask:0xf bank_mask:0xf
	v_fmac_f32_e32 v81, v72, v80
	v_fmac_f32_e32 v81, v40, v76
	v_mul_f32_e32 v40, 0xbfb8aa3b, v81
	v_exp_f32_e32 v40, v40
	s_nop 0
	v_mov_b32_dpp v44, v36 row_ror:1 row_mask:0xf bank_mask:0xf
	v_mov_b32_dpp v80, v36 row_ror:2 row_mask:0xf bank_mask:0xf
	v_add_f32_e32 v36, 1.0, v40
	v_rcp_f32_e32 v36, v36
	v_mov_b32_dpp v80, v32 row_shr:2 row_mask:0xf bank_mask:0xf
	v_mov_b32_dpp v44, v32 row_shr:1 row_mask:0xf bank_mask:0xf
	v_fma_f32 v40, v48, v80, v64
	v_fmac_f32_e32 v40, v52, v44
	v_fmac_f32_e32 v40, v32, v56
	v_mul_f32_e32 v32, v81, v36
	v_mul_f32_e32 v32, v40, v32
	v_mov_b32_dpp v40, v45 row_ror:2 row_mask:0xf bank_mask:0xf
	v_mov_b32_dpp v36, v45 row_ror:1 row_mask:0xf bank_mask:0xf
	v_mov_b32_dpp v44, v37 row_ror:1 row_mask:0xf bank_mask:0xf
	v_mov_b32_dpp v40, v41 row_shr:2 row_mask:0xf bank_mask:0xf
	v_mov_b32_dpp v36, v41 row_shr:1 row_mask:0xf bank_mask:0xf
	v_fma_f32 v40, v69, v40, v61
	v_fmac_f32_e32 v40, v73, v36
	v_fmac_f32_e32 v40, v41, v77
	v_mul_f32_e32 v36, 0xbfb8aa3b, v40
	v_exp_f32_e32 v36, v36
	v_mov_b32_dpp v44, v33 row_shr:1 row_mask:0xf bank_mask:0xf
	v_add_f32_e32 v36, 1.0, v36
	v_mov_b32_dpp v41, v37 row_ror:2 row_mask:0xf bank_mask:0xf
	v_rcp_f32_e32 v36, v36
	s_nop 0
	v_mov_b32_dpp v41, v33 row_shr:2 row_mask:0xf bank_mask:0xf
	v_fma_f32 v37, v49, v41, v65
	v_fmac_f32_e32 v37, v53, v44
	v_fmac_f32_e32 v37, v33, v57
	v_mul_f32_e32 v33, v40, v36
	v_mul_f32_e32 v33, v37, v33
	v_mov_b32_dpp v37, v46 row_ror:2 row_mask:0xf bank_mask:0xf
	v_mov_b32_dpp v36, v46 row_ror:1 row_mask:0xf bank_mask:0xf
	v_mov_b32_dpp v37, v42 row_shr:2 row_mask:0xf bank_mask:0xf
	v_mov_b32_dpp v36, v42 row_shr:1 row_mask:0xf bank_mask:0xf
	v_fma_f32 v37, v70, v37, v62
	v_fmac_f32_e32 v37, v74, v36
	v_fmac_f32_e32 v37, v42, v78
	v_mul_f32_e32 v36, 0xbfb8aa3b, v37
	v_exp_f32_e32 v36, v36
	v_mov_b32_dpp v41, v38 row_ror:2 row_mask:0xf bank_mask:0xf
	v_mov_b32_dpp v40, v38 row_ror:1 row_mask:0xf bank_mask:0xf
	v_cvt_pk_bf16_f32 v146, v32, v33
	v_add_f32_e32 v36, 1.0, v36
	v_rcp_f32_e32 v36, v36
	v_mov_b32_dpp v41, v34 row_shr:2 row_mask:0xf bank_mask:0xf
	v_mov_b32_dpp v40, v34 row_shr:1 row_mask:0xf bank_mask:0xf
	v_fma_f32 v38, v50, v41, v66
	v_fmac_f32_e32 v38, v54, v40
	v_fmac_f32_e32 v38, v34, v58
	v_mul_f32_e32 v34, v37, v36
	v_mov_b32_dpp v37, v47 row_ror:2 row_mask:0xf bank_mask:0xf
	v_mov_b32_dpp v36, v47 row_ror:1 row_mask:0xf bank_mask:0xf
	v_mul_f32_e32 v34, v38, v34
	v_mov_b32_dpp v37, v43 row_shr:2 row_mask:0xf bank_mask:0xf
	v_mov_b32_dpp v36, v43 row_shr:1 row_mask:0xf bank_mask:0xf
	v_fma_f32 v37, v71, v37, v63
	v_fmac_f32_e32 v37, v75, v36
	v_fmac_f32_e32 v37, v43, v79
	v_mul_f32_e32 v36, 0xbfb8aa3b, v37
	v_exp_f32_e32 v36, v36
	v_mov_b32_dpp v40, v39 row_ror:2 row_mask:0xf bank_mask:0xf
	v_add_f32_e32 v36, 1.0, v36
	v_rcp_f32_e32 v36, v36
	v_mov_b32_dpp v38, v39 row_ror:1 row_mask:0xf bank_mask:0xf
	v_mov_b32_dpp v40, v35 row_shr:2 row_mask:0xf bank_mask:0xf
	v_fma_f32 v39, v51, v40, v67
	v_mov_b32_dpp v38, v35 row_shr:1 row_mask:0xf bank_mask:0xf
	v_fmac_f32_e32 v39, v55, v38
	v_fmac_f32_e32 v39, v35, v59
	v_mul_f32_e32 v35, v37, v36
	v_mul_f32_e32 v35, v39, v35
	v_cvt_pk_bf16_f32 v147, v34, v35
	v_mov_b32_e32 v144, v226
	v_mov_b32_e32 v145, v227
	global_store_dwordx4 v[134:135], v[144:147], off sc1
	v_mov_b32_e32 v32, 0
	v_mov_b32_e32 v33, 0
	v_mov_b32_e32 v34, 0
	v_mov_b32_e32 v35, 0
	s_and_saveexec_b64 s[54:55], s[4:5]
	s_cbranch_execz .LBB0_721
	ds_read_b128 v[128:131], v237
	ds_read_b128 v[32:35], v236
.LBB0_721:
	s_or_b64 exec, exec, s[54:55]
	s_waitcnt lgkmcnt(1)
	v_mov_b32_dpp v37, v128 row_ror:2 row_mask:0xf bank_mask:0xf
	v_mov_b32_dpp v36, v128 row_ror:1 row_mask:0xf bank_mask:0xf
	v_mov_b32_dpp v37, v28 row_shr:2 row_mask:0xf bank_mask:0xf
	v_mov_b32_dpp v36, v28 row_shr:1 row_mask:0xf bank_mask:0xf
	v_fma_f32 v37, v68, v37, v60
	v_fmac_f32_e32 v37, v72, v36
	v_fmac_f32_e32 v37, v28, v76
	v_mul_f32_e32 v36, 0xbfb8aa3b, v37
	v_exp_f32_e32 v36, v36
	s_waitcnt lgkmcnt(0)
	v_mov_b32_dpp v38, v32 row_ror:1 row_mask:0xf bank_mask:0xf
	v_mov_b32_dpp v39, v32 row_ror:2 row_mask:0xf bank_mask:0xf
	s_andn2_b64 vcc, exec, s[8:9]
	v_add_f32_e32 v32, 1.0, v36
	v_rcp_f32_e32 v32, v32
	v_mov_b32_dpp v39, v24 row_shr:2 row_mask:0xf bank_mask:0xf
	v_mov_b32_dpp v38, v24 row_shr:1 row_mask:0xf bank_mask:0xf
	v_fma_f32 v36, v48, v39, v64
	v_fmac_f32_e32 v36, v52, v38
	v_fmac_f32_e32 v36, v24, v56
	v_mul_f32_e32 v32, v37, v32
	v_mul_f32_e32 v32, v36, v32
	v_mov_b32_dpp v37, v129 row_ror:2 row_mask:0xf bank_mask:0xf
	v_mov_b32_dpp v36, v129 row_ror:1 row_mask:0xf bank_mask:0xf
	v_mov_b32_dpp v37, v29 row_shr:2 row_mask:0xf bank_mask:0xf
	v_fma_f32 v37, v69, v37, v61
	v_mov_b32_dpp v36, v29 row_shr:1 row_mask:0xf bank_mask:0xf
	v_fmac_f32_e32 v37, v73, v36
	v_fmac_f32_e32 v37, v29, v77
	v_mul_f32_e32 v36, 0xbfb8aa3b, v37
	v_exp_f32_e32 v36, v36
	v_mov_b32_dpp v38, v33 row_ror:1 row_mask:0xf bank_mask:0xf
	s_mov_b64 s[8:9], -1
	v_mov_b32_dpp v39, v33 row_ror:2 row_mask:0xf bank_mask:0xf
	v_add_f32_e32 v33, 1.0, v36
	v_rcp_f32_e32 v33, v33
	v_mov_b32_dpp v39, v25 row_shr:2 row_mask:0xf bank_mask:0xf
	v_mov_b32_dpp v38, v25 row_shr:1 row_mask:0xf bank_mask:0xf
	v_fma_f32 v36, v49, v39, v65
	v_fmac_f32_e32 v36, v53, v38
	v_fmac_f32_e32 v36, v25, v57
	v_mul_f32_e32 v33, v37, v33
	v_mul_f32_e32 v33, v36, v33
	v_mov_b32_dpp v37, v130 row_ror:2 row_mask:0xf bank_mask:0xf
	v_mov_b32_dpp v36, v130 row_ror:1 row_mask:0xf bank_mask:0xf
	v_mov_b32_dpp v37, v30 row_shr:2 row_mask:0xf bank_mask:0xf
	v_fma_f32 v37, v70, v37, v62
	v_mov_b32_dpp v36, v30 row_shr:1 row_mask:0xf bank_mask:0xf
	v_fmac_f32_e32 v37, v74, v36
	v_fmac_f32_e32 v37, v30, v78
	v_mul_f32_e32 v36, 0xbfb8aa3b, v37
	v_exp_f32_e32 v36, v36
	v_mov_b32_dpp v38, v34 row_ror:1 row_mask:0xf bank_mask:0xf
	v_cvt_pk_bf16_f32 v146, v32, v33
	v_mov_b32_dpp v39, v34 row_ror:2 row_mask:0xf bank_mask:0xf
	v_add_f32_e32 v34, 1.0, v36
	v_rcp_f32_e32 v34, v34
	v_mov_b32_dpp v39, v26 row_shr:2 row_mask:0xf bank_mask:0xf
	v_mov_b32_dpp v38, v26 row_shr:1 row_mask:0xf bank_mask:0xf
	v_fma_f32 v36, v50, v39, v66
	v_fmac_f32_e32 v36, v54, v38
	v_fmac_f32_e32 v36, v26, v58
	v_mul_f32_e32 v34, v37, v34
	v_mul_f32_e32 v34, v36, v34
	v_mov_b32_dpp v37, v131 row_ror:2 row_mask:0xf bank_mask:0xf
	v_mov_b32_dpp v36, v131 row_ror:1 row_mask:0xf bank_mask:0xf
	v_mov_b32_dpp v37, v31 row_shr:2 row_mask:0xf bank_mask:0xf
	v_fma_f32 v37, v71, v37, v63
	v_mov_b32_dpp v36, v31 row_shr:1 row_mask:0xf bank_mask:0xf
	v_fmac_f32_e32 v37, v75, v36
	v_fmac_f32_e32 v37, v31, v79
	v_mul_f32_e32 v36, 0xbfb8aa3b, v37
	v_exp_f32_e32 v36, v36
	v_mov_b32_dpp v38, v35 row_ror:1 row_mask:0xf bank_mask:0xf
	v_mov_b32_dpp v39, v35 row_ror:2 row_mask:0xf bank_mask:0xf
	v_add_f32_e32 v35, 1.0, v36
	v_rcp_f32_e32 v35, v35
	v_mov_b32_dpp v39, v27 row_shr:2 row_mask:0xf bank_mask:0xf
	v_mov_b32_dpp v38, v27 row_shr:1 row_mask:0xf bank_mask:0xf
	v_fma_f32 v36, v51, v39, v67
	v_fmac_f32_e32 v36, v55, v38
	v_fmac_f32_e32 v36, v27, v59
	v_mul_f32_e32 v35, v37, v35
	v_mul_f32_e32 v35, v36, v35
	v_cvt_pk_bf16_f32 v147, v34, v35
	v_mov_b32_e32 v144, v186
	v_mov_b32_e32 v145, v187
	global_store_dwordx4 v[132:133], v[144:147], off sc1
	v_mov_b32_dpp v33, v28 row_ror:2 row_mask:0xf bank_mask:0xf
	v_mov_b32_dpp v32, v28 row_ror:1 row_mask:0xf bank_mask:0xf
	v_mov_b32_dpp v33, v20 row_shr:2 row_mask:0xf bank_mask:0xf
	v_fma_f32 v33, v68, v33, v60
	v_mov_b32_dpp v32, v20 row_shr:1 row_mask:0xf bank_mask:0xf
	v_fmac_f32_e32 v33, v72, v32
	v_fmac_f32_e32 v33, v20, v76
	v_mul_f32_e32 v32, 0xbfb8aa3b, v33
	v_exp_f32_e32 v32, v32
	v_mov_b32_dpp v34, v24 row_ror:2 row_mask:0xf bank_mask:0xf
	s_nop 0
	v_mov_b32_dpp v28, v24 row_ror:1 row_mask:0xf bank_mask:0xf
	v_add_f32_e32 v24, 1.0, v32
	v_rcp_f32_e32 v24, v24
	v_mov_b32_dpp v34, v16 row_shr:2 row_mask:0xf bank_mask:0xf
	v_mov_b32_dpp v28, v16 row_shr:1 row_mask:0xf bank_mask:0xf
	v_fma_f32 v32, v48, v34, v64
	v_fmac_f32_e32 v32, v52, v28
	v_fmac_f32_e32 v32, v16, v56
	v_mul_f32_e32 v24, v33, v24
	v_mul_f32_e32 v24, v32, v24
	v_mov_b32_dpp v32, v29 row_ror:2 row_mask:0xf bank_mask:0xf
	v_mov_b32_dpp v28, v29 row_ror:1 row_mask:0xf bank_mask:0xf
	v_mov_b32_dpp v32, v21 row_shr:2 row_mask:0xf bank_mask:0xf
	v_mov_b32_dpp v28, v21 row_shr:1 row_mask:0xf bank_mask:0xf
	v_fma_f32 v32, v69, v32, v61
	v_fmac_f32_e32 v32, v73, v28
	v_fmac_f32_e32 v32, v21, v77
	v_mul_f32_e32 v28, 0xbfb8aa3b, v32
	v_exp_f32_e32 v28, v28
	v_mov_b32_dpp v29, v25 row_ror:1 row_mask:0xf bank_mask:0xf
	v_mov_b32_dpp v33, v25 row_ror:2 row_mask:0xf bank_mask:0xf
	v_add_f32_e32 v25, 1.0, v28
	v_rcp_f32_e32 v25, v25
	v_mov_b32_dpp v33, v17 row_shr:2 row_mask:0xf bank_mask:0xf
	v_mov_b32_dpp v29, v17 row_shr:1 row_mask:0xf bank_mask:0xf
	v_fma_f32 v28, v49, v33, v65
	v_fmac_f32_e32 v28, v53, v29
	v_fmac_f32_e32 v28, v17, v57
	v_mul_f32_e32 v25, v32, v25
	v_mul_f32_e32 v25, v28, v25
	v_mov_b32_dpp v29, v30 row_ror:2 row_mask:0xf bank_mask:0xf
	v_mov_b32_dpp v28, v30 row_ror:1 row_mask:0xf bank_mask:0xf
	v_mov_b32_dpp v29, v22 row_shr:2 row_mask:0xf bank_mask:0xf
	v_fma_f32 v29, v70, v29, v62
	v_mov_b32_dpp v28, v22 row_shr:1 row_mask:0xf bank_mask:0xf
	v_fmac_f32_e32 v29, v74, v28
	v_fmac_f32_e32 v29, v22, v78
	v_mul_f32_e32 v28, 0xbfb8aa3b, v29
	v_exp_f32_e32 v28, v28
	v_mov_b32_dpp v32, v26 row_ror:2 row_mask:0xf bank_mask:0xf
	v_cvt_pk_bf16_f32 v146, v24, v25
	v_mov_b32_dpp v30, v26 row_ror:1 row_mask:0xf bank_mask:0xf
	v_add_f32_e32 v26, 1.0, v28
	v_rcp_f32_e32 v26, v26
	v_mov_b32_dpp v32, v18 row_shr:2 row_mask:0xf bank_mask:0xf
	v_mov_b32_dpp v30, v18 row_shr:1 row_mask:0xf bank_mask:0xf
	v_fma_f32 v28, v50, v32, v66
	v_fmac_f32_e32 v28, v54, v30
	v_fmac_f32_e32 v28, v18, v58
	v_mul_f32_e32 v26, v29, v26
	v_mul_f32_e32 v26, v28, v26
	v_mov_b32_dpp v29, v31 row_ror:2 row_mask:0xf bank_mask:0xf
	v_mov_b32_dpp v28, v31 row_ror:1 row_mask:0xf bank_mask:0xf
	v_mov_b32_dpp v29, v23 row_shr:2 row_mask:0xf bank_mask:0xf
	v_fma_f32 v29, v71, v29, v63
	v_mov_b32_dpp v28, v23 row_shr:1 row_mask:0xf bank_mask:0xf
	v_fmac_f32_e32 v29, v75, v28
	v_fmac_f32_e32 v29, v23, v79
	v_mul_f32_e32 v28, 0xbfb8aa3b, v29
	v_exp_f32_e32 v28, v28
	v_mov_b32_dpp v30, v27 row_ror:1 row_mask:0xf bank_mask:0xf
	v_mov_b32_dpp v31, v27 row_ror:2 row_mask:0xf bank_mask:0xf
	v_add_f32_e32 v27, 1.0, v28
	v_rcp_f32_e32 v27, v27
	v_mov_b32_dpp v31, v19 row_shr:2 row_mask:0xf bank_mask:0xf
	v_mov_b32_dpp v30, v19 row_shr:1 row_mask:0xf bank_mask:0xf
	v_fma_f32 v28, v51, v31, v67
	v_fmac_f32_e32 v28, v55, v30
	v_fmac_f32_e32 v28, v19, v59
	v_mul_f32_e32 v27, v29, v27
	v_mul_f32_e32 v27, v28, v27
	v_cvt_pk_bf16_f32 v147, v26, v27
	v_mov_b32_e32 v144, v188
	v_mov_b32_e32 v145, v189
	global_store_dwordx4 v[120:121], v[144:147], off sc1
	v_mov_b32_dpp v25, v20 row_ror:2 row_mask:0xf bank_mask:0xf
	v_mov_b32_dpp v24, v20 row_ror:1 row_mask:0xf bank_mask:0xf
	v_mov_b32_dpp v25, v12 row_shr:2 row_mask:0xf bank_mask:0xf
	v_fma_f32 v25, v68, v25, v60
	v_mov_b32_dpp v24, v12 row_shr:1 row_mask:0xf bank_mask:0xf
	v_fmac_f32_e32 v25, v72, v24
	v_fmac_f32_e32 v25, v12, v76
	v_mul_f32_e32 v24, 0xbfb8aa3b, v25
	v_exp_f32_e32 v24, v24
	v_mov_b32_dpp v26, v16 row_ror:2 row_mask:0xf bank_mask:0xf
	s_nop 0
	v_mov_b32_dpp v20, v16 row_ror:1 row_mask:0xf bank_mask:0xf
	v_add_f32_e32 v16, 1.0, v24
	v_rcp_f32_e32 v16, v16
	v_mov_b32_dpp v26, v4 row_shr:2 row_mask:0xf bank_mask:0xf
	v_mov_b32_dpp v20, v4 row_shr:1 row_mask:0xf bank_mask:0xf
	v_fma_f32 v24, v48, v26, v64
	v_fmac_f32_e32 v24, v52, v20
	v_fmac_f32_e32 v24, v4, v56
	v_mul_f32_e32 v16, v25, v16
	v_mul_f32_e32 v16, v24, v16
	v_mov_b32_dpp v24, v21 row_ror:2 row_mask:0xf bank_mask:0xf
	v_mov_b32_dpp v20, v21 row_ror:1 row_mask:0xf bank_mask:0xf
	v_mov_b32_dpp v24, v13 row_shr:2 row_mask:0xf bank_mask:0xf
	v_mov_b32_dpp v20, v13 row_shr:1 row_mask:0xf bank_mask:0xf
	v_fma_f32 v24, v69, v24, v61
	v_fmac_f32_e32 v24, v73, v20
	v_fmac_f32_e32 v24, v13, v77
	v_mul_f32_e32 v20, 0xbfb8aa3b, v24
	v_exp_f32_e32 v20, v20
	v_mov_b32_dpp v21, v17 row_ror:1 row_mask:0xf bank_mask:0xf
	v_mov_b32_dpp v25, v17 row_ror:2 row_mask:0xf bank_mask:0xf
	v_add_f32_e32 v17, 1.0, v20
	v_rcp_f32_e32 v17, v17
	v_mov_b32_dpp v25, v5 row_shr:2 row_mask:0xf bank_mask:0xf
	v_mov_b32_dpp v21, v5 row_shr:1 row_mask:0xf bank_mask:0xf
	v_fma_f32 v20, v49, v25, v65
	v_fmac_f32_e32 v20, v53, v21
	v_fmac_f32_e32 v20, v5, v57
	v_mul_f32_e32 v17, v24, v17
	v_mul_f32_e32 v17, v20, v17
	v_mov_b32_dpp v21, v22 row_ror:2 row_mask:0xf bank_mask:0xf
	v_mov_b32_dpp v20, v22 row_ror:1 row_mask:0xf bank_mask:0xf
	v_mov_b32_dpp v21, v14 row_shr:2 row_mask:0xf bank_mask:0xf
	v_fma_f32 v21, v70, v21, v62
	v_mov_b32_dpp v20, v14 row_shr:1 row_mask:0xf bank_mask:0xf
	v_fmac_f32_e32 v21, v74, v20
	v_fmac_f32_e32 v21, v14, v78
	v_mul_f32_e32 v20, 0xbfb8aa3b, v21
	v_exp_f32_e32 v20, v20
	v_mov_b32_dpp v24, v18 row_ror:2 row_mask:0xf bank_mask:0xf
	v_cvt_pk_bf16_f32 v146, v16, v17
	v_mov_b32_dpp v22, v18 row_ror:1 row_mask:0xf bank_mask:0xf
	v_add_f32_e32 v18, 1.0, v20
	v_rcp_f32_e32 v18, v18
	v_mov_b32_dpp v24, v6 row_shr:2 row_mask:0xf bank_mask:0xf
	v_mov_b32_dpp v22, v6 row_shr:1 row_mask:0xf bank_mask:0xf
	v_fma_f32 v20, v50, v24, v66
	v_fmac_f32_e32 v20, v54, v22
	v_fmac_f32_e32 v20, v6, v58
	v_mul_f32_e32 v18, v21, v18
	v_mul_f32_e32 v18, v20, v18
	v_mov_b32_dpp v21, v23 row_ror:2 row_mask:0xf bank_mask:0xf
	v_mov_b32_dpp v20, v23 row_ror:1 row_mask:0xf bank_mask:0xf
	v_mov_b32_dpp v21, v15 row_shr:2 row_mask:0xf bank_mask:0xf
	v_fma_f32 v21, v71, v21, v63
	v_mov_b32_dpp v20, v15 row_shr:1 row_mask:0xf bank_mask:0xf
	v_fmac_f32_e32 v21, v75, v20
	v_fmac_f32_e32 v21, v15, v79
	v_mul_f32_e32 v20, 0xbfb8aa3b, v21
	v_exp_f32_e32 v20, v20
	v_mov_b32_dpp v22, v19 row_ror:1 row_mask:0xf bank_mask:0xf
	v_mov_b32_dpp v23, v19 row_ror:2 row_mask:0xf bank_mask:0xf
	v_add_f32_e32 v19, 1.0, v20
	v_rcp_f32_e32 v19, v19
	v_mov_b32_dpp v23, v7 row_shr:2 row_mask:0xf bank_mask:0xf
	v_mov_b32_dpp v22, v7 row_shr:1 row_mask:0xf bank_mask:0xf
	v_fma_f32 v20, v51, v23, v67
	v_fmac_f32_e32 v20, v55, v22
	v_fmac_f32_e32 v20, v7, v59
	v_mul_f32_e32 v19, v21, v19
	v_mul_f32_e32 v19, v20, v19
	v_cvt_pk_bf16_f32 v147, v18, v19
	v_mov_b32_e32 v144, v190
	v_mov_b32_e32 v145, v191
	global_store_dwordx4 v[112:113], v[144:147], off sc1
	v_mov_b32_dpp v17, v12 row_ror:2 row_mask:0xf bank_mask:0xf
	s_nop 0
	v_mov_b32_dpp v16, v12 row_ror:1 row_mask:0xf bank_mask:0xf
	v_mov_b32_dpp v17, v8 row_shr:2 row_mask:0xf bank_mask:0xf
	v_fma_f32 v17, v68, v17, v60
	v_mov_b32_dpp v16, v8 row_shr:1 row_mask:0xf bank_mask:0xf
	v_fmac_f32_e32 v17, v72, v16
	v_fmac_f32_e32 v17, v8, v76
	v_mul_f32_e32 v8, 0xbfb8aa3b, v17
	v_exp_f32_e32 v8, v8
	s_nop 0
	v_mov_b32_dpp v12, v4 row_ror:1 row_mask:0xf bank_mask:0xf
	v_mov_b32_dpp v16, v4 row_ror:2 row_mask:0xf bank_mask:0xf
	v_add_f32_e32 v4, 1.0, v8
	v_rcp_f32_e32 v4, v4
	v_mov_b32_dpp v16, v0 row_shr:2 row_mask:0xf bank_mask:0xf
	v_mov_b32_dpp v12, v0 row_shr:1 row_mask:0xf bank_mask:0xf
	v_fma_f32 v8, v48, v16, v64
	v_fmac_f32_e32 v8, v52, v12
	v_fmac_f32_e32 v8, v0, v56
	v_mul_f32_e32 v0, v17, v4
	v_mul_f32_e32 v0, v8, v0
	v_mov_b32_dpp v8, v13 row_ror:2 row_mask:0xf bank_mask:0xf
	v_mov_b32_dpp v4, v13 row_ror:1 row_mask:0xf bank_mask:0xf
	v_mov_b32_dpp v12, v5 row_ror:1 row_mask:0xf bank_mask:0xf
	v_mov_b32_dpp v8, v9 row_shr:2 row_mask:0xf bank_mask:0xf
	v_mov_b32_dpp v4, v9 row_shr:1 row_mask:0xf bank_mask:0xf
	v_fma_f32 v8, v69, v8, v61
	v_fmac_f32_e32 v8, v73, v4
	v_fmac_f32_e32 v8, v9, v77
	v_mul_f32_e32 v4, 0xbfb8aa3b, v8
	v_exp_f32_e32 v4, v4
	v_mov_b32_dpp v12, v1 row_shr:1 row_mask:0xf bank_mask:0xf
	v_add_f32_e32 v4, 1.0, v4
	v_mov_b32_dpp v9, v5 row_ror:2 row_mask:0xf bank_mask:0xf
	v_rcp_f32_e32 v4, v4
	s_nop 0
	v_mov_b32_dpp v9, v1 row_shr:2 row_mask:0xf bank_mask:0xf
	v_fma_f32 v5, v49, v9, v65
	v_fmac_f32_e32 v5, v53, v12
	v_fmac_f32_e32 v5, v1, v57
	v_mul_f32_e32 v1, v8, v4
	v_mul_f32_e32 v1, v5, v1
	v_mov_b32_dpp v5, v14 row_ror:2 row_mask:0xf bank_mask:0xf
	v_mov_b32_dpp v4, v14 row_ror:1 row_mask:0xf bank_mask:0xf
	v_mov_b32_dpp v5, v10 row_shr:2 row_mask:0xf bank_mask:0xf
	v_mov_b32_dpp v4, v10 row_shr:1 row_mask:0xf bank_mask:0xf
	v_fma_f32 v5, v70, v5, v62
	v_fmac_f32_e32 v5, v74, v4
	v_fmac_f32_e32 v5, v10, v78
	v_mul_f32_e32 v4, 0xbfb8aa3b, v5
	v_exp_f32_e32 v4, v4
	v_mov_b32_dpp v9, v6 row_ror:2 row_mask:0xf bank_mask:0xf
	v_mov_b32_dpp v8, v6 row_ror:1 row_mask:0xf bank_mask:0xf
	v_cvt_pk_bf16_f32 v146, v0, v1
	v_add_f32_e32 v4, 1.0, v4
	v_rcp_f32_e32 v4, v4
	v_mov_b32_dpp v9, v2 row_shr:2 row_mask:0xf bank_mask:0xf
	v_mov_b32_dpp v8, v2 row_shr:1 row_mask:0xf bank_mask:0xf
	v_fma_f32 v6, v50, v9, v66
	v_fmac_f32_e32 v6, v54, v8
	v_fmac_f32_e32 v6, v2, v58
	v_mul_f32_e32 v2, v5, v4
	v_mul_f32_e32 v2, v6, v2
	v_mov_b32_dpp v5, v15 row_ror:2 row_mask:0xf bank_mask:0xf
	v_mov_b32_dpp v4, v15 row_ror:1 row_mask:0xf bank_mask:0xf
	v_mov_b32_dpp v5, v11 row_shr:2 row_mask:0xf bank_mask:0xf
	v_mov_b32_dpp v4, v11 row_shr:1 row_mask:0xf bank_mask:0xf
	v_fmac_f32_e32 v63, v71, v5
	v_fmac_f32_e32 v63, v75, v4
	v_fmac_f32_e32 v63, v11, v79
	v_mul_f32_e32 v4, 0xbfb8aa3b, v63
	v_exp_f32_e32 v4, v4
	v_mov_b32_dpp v6, v7 row_ror:1 row_mask:0xf bank_mask:0xf
	v_add_f32_e32 v4, 1.0, v4
	v_mov_b32_dpp v5, v7 row_ror:2 row_mask:0xf bank_mask:0xf
	v_rcp_f32_e32 v4, v4
	v_mov_b32_dpp v6, v3 row_shr:1 row_mask:0xf bank_mask:0xf
	v_mov_b32_dpp v5, v3 row_shr:2 row_mask:0xf bank_mask:0xf
	v_fmac_f32_e32 v67, v51, v5
	v_fmac_f32_e32 v67, v55, v6
	v_fmac_f32_e32 v67, v3, v59
	v_mul_f32_e32 v3, v63, v4
	v_mul_f32_e32 v3, v67, v3
	v_cvt_pk_bf16_f32 v147, v2, v3
	v_mov_b32_e32 v144, v192
	v_mov_b32_e32 v145, v193
	global_store_dwordx4 v[104:105], v[144:147], off sc1
	s_cbranch_vccnz .LBB0_701
	s_and_b64 vcc, exec, s[10:11]
	s_cbranch_vccnz .LBB0_700
	s_barrier
	s_branch .LBB0_700
	s_nop 0
	s_nop 0
	s_nop 0
	s_nop 0
	s_nop 0
	s_nop 0
	s_nop 0
	s_nop 0
	s_nop 0
	s_nop 0
	s_nop 0
	s_nop 0
	s_nop 0
	s_nop 0
	s_nop 0
	s_nop 0
	s_nop 0
	s_nop 0
	s_nop 0
	s_nop 0
	s_nop 0
	s_nop 0
	s_nop 0
	s_nop 0
	s_nop 0
	s_nop 0
	s_nop 0
	s_nop 0
	s_nop 0
	s_nop 0
	s_nop 0
	s_nop 0
	s_nop 0
	s_nop 0
	s_nop 0
	s_nop 0
	s_nop 0
	s_nop 0
	s_nop 0
	s_nop 0
	s_nop 0
	s_nop 0
	s_nop 0
	s_nop 0
	s_nop 0
	s_nop 0
	s_nop 0
	s_nop 0
	s_nop 0
	s_nop 0
	s_nop 0
	s_nop 0
	s_nop 0
	s_nop 0
	s_nop 0
	s_nop 0
	s_nop 0
	s_nop 0
	s_nop 0
	s_nop 0
	s_nop 0
	s_nop 0
	s_nop 0
	s_nop 0
	s_nop 0
	s_nop 0
	s_nop 0
	s_nop 0
	s_nop 0
	s_nop 0
	s_nop 0
	s_nop 0
	s_nop 0
	s_nop 0
	s_nop 0
	s_nop 0
	s_nop 0
	s_nop 0
	s_nop 0
	s_nop 0
	s_nop 0
	s_nop 0
	s_nop 0
	s_nop 0
	s_nop 0
	s_nop 0
	s_nop 0
	s_nop 0
	s_nop 0
	s_nop 0
	s_nop 0
	s_nop 0
	s_nop 0
	s_nop 0
